# GEMM unit transitions: the trailing wave group runs its epilogue before (not after) its closing barrier on the last K-iteration, overlapping both groups' epilogues
# baseline (speedup 1.0000x reference)
; __device__ __forceinline__ unsigned pk2(float lo, float hi) { unsigned r; asm("v_cvt_pk_bf16_f32 %0, %1, %2" : "=v"(r) : "v"(lo), "v"(hi)); return r; }
; __device__ __forceinline__ float gelu_t(float x) { return x * __builtin_amdgcn_rcpf(1.f + __expf(-1.5957691216057308f * (x + 0.044715f * x * x * x))); }
;     __device__ __forceinline__ void operator()(const f32x4 (&acc)[2][2][4][2], const Unit& u, int wr, int wc, int fr, int fq) const {
;     ...
;             for (int m = 0; m < 4; ++m) { const int row = row0 + ai * HALF + m * 16; u16* rowp = O + (size_t)row * ldc + col0;
; #pragma unroll
;                 for (int bj = 0; bj < 2; ++bj) { f32x4 v0 = acc[ai][bj][m][0], v1 = acc[ai][bj][m][1];
;                     if (col0 + bj * HALF >= gelu_from) { v0 = (f32x4){gelu_t(v0.x), gelu_t(v0.y), gelu_t(v0.z), gelu_t(v0.w)}; v1 = (f32x4){gelu_t(v1.x), gelu_t(v1.y), gelu_t(v1.z), gelu_t(v1.w)}; }
;                     u32x4 w; w.x = pk2(v0[0], v0[1]); w.y = pk2(v0[2], v0[3]); w.z = pk2(v1[0], v1[1]); w.w = pk2(v1[2], v1[3]);
;                     *(u32x4*)(rowp + bj * HALF) = w;
;                     if (halo != nullptr && m == 3 && fr >= 14) *(u32x4*)(halo + (size_t)((row >> 6) * 2 + (fr - 14)) * ldc + col0 + bj * HALF) = w; } }
; template <class Epi>
; __device__ __forceinline__ void gemm_phase(LAS unsigned char* lds, const Gemm g, const StaticOrder& S, const Epi& E) {
;     ...
;         E(acc, cur, wr, wc, fr, fq);
;         if (!has_next) break;
.LBB0_111:
	s_or_b64 exec, exec, s[60:61]
	s_cmpk_gt_u32 s3, 0xff
	s_cbranch_scc0 .Leo_l0
	s_barrier
.Leo_l0:
	s_and_b64 vcc, exec, s[6:7]
	s_mov_b32 s60, s30
	s_mov_b32 s8, s54
	s_mov_b64 s[64:65], s[58:59]
	s_mov_b64 s[62:63], s[56:57]
	v_cvt_pk_bf16_f32 v4, v4, v5
	v_cvt_pk_bf16_f32 v5, v6, v7
	v_cvt_pk_bf16_f32 v6, v0, v1
	v_cvt_pk_bf16_f32 v7, v2, v3
	global_store_dwordx4 v[16:17], v[4:7], off offset:256
	s_cbranch_vccnz .LBB0_152

; #define PG8_STAGE(bufoff, gbase, voff) do { _Pragma("unroll") for (int _i = 0; _i < 2; ++_i) \
;         __builtin_amdgcn_global_load_lds((const unsigned*)((const char*)(gbase) + (voff)[_i]), (LAS unsigned*)(lds + (bufoff) + ldsw + _i * 8192), 16, 0, 0); } while (0)
; #define PG8_LDA(dst, b, h) do { _Pragma("unroll") for (int m = 0; m < 4; ++m) _Pragma("unroll") for (int k = 0; k < 2; ++k) dst[m][k] = *(const LAS bf16x8*)(lds + PG8_SA(b, h) + aoff + m * 2048 + k * 1024); } while (0)
; #define PG8_LDB(dst, b, h) do { _Pragma("unroll") for (int n = 0; n < 2; ++n) _Pragma("unroll") for (int k = 0; k < 2; ++k) dst[n][k] = *(const LAS bf16x8*)(lds + PG8_SB(b, h) + boff + n * 2048 + k * 1024); } while (0)
; #define PG8_MMA(ai, bj, At, Bt) do { __builtin_amdgcn_s_setprio(1); _Pragma("unroll") for (int m = 0; m < 4; ++m) _Pragma("unroll") for (int n = 0; n < 2; ++n) _Pragma("unroll") for (int k = 0; k < 2; ++k) \
;         acc[ai][bj][m][n] = __builtin_amdgcn_mfma_f32_16x16x32_bf16(Bt[n][k], At[m][k], acc[ai][bj][m][n], 0, 0, 0); __builtin_amdgcn_s_setprio(0); } while (0)
; #define PG8_BAR __builtin_amdgcn_s_barrier()
; template <class Epi>
; __device__ __forceinline__ void gemm_phase(LAS unsigned char* lds, const Gemm g, const StaticOrder& S, const Epi& E) {
;     ...
;         const char* nA = has_next ? (const char*)g.A + (size_t)nxt.pm * tstepA + (size_t)nxt.kt0 * kstep : cA; const char* nB = has_next ? (const char*)g.Bt + (size_t)nxt.pn * tstepB + (size_t)nxt.kt0 * kstep : cB;
;         const int nt = cur.nkt;
;         for (int t = 0; t < nt; t += 2) {
;             const bool last = (t == nt - 2);
;             const char* a1 = cA + (size_t)(t + 1) * kstep;
;             const char* a2 = last ? nA : cA + (size_t)(t + 2) * kstep; const char* b2 = last ? nB : cB + (size_t)(t + 2) * kstep;
;             const char* a3 = a2 + kstep; const char* b3 = b2 + kstep;
;             PG8_LDB(B0, 0, 0); PG8_SCHED; PG8_LDA(At, 0, 0); PG8_STAGE(PG8_SA(1, 1), a1 + hstepA, voffA);
;             PG8_WAIT_L(8); PG8_BAR; PG8_WAIT_L(0); PG8_MMA(0, 0, At, B0); PG8_BAR; PG8_SCHED;
;             PG8_LDB(B1, 0, 1); PG8_STAGE(PG8_SB(0, 0), b2, voffB);
;             PG8_BAR; PG8_WAIT_L(0); PG8_MMA(0, 1, At, B1); PG8_BAR;
;             PG8_LDA(At, 0, 1); PG8_STAGE(PG8_SA(0, 0), a2, voffA);
;             PG8_BAR; PG8_WAIT_L(0); PG8_MMA(1, 0, At, B0); PG8_BAR; PG8_SCHED;
.LBB0_119:
	s_add_u32 s55, s62, 0xfffc0080
	s_addc_u32 s61, s63, -1
	s_cmp_eq_u32 s33, 12
	s_cselect_b32 s67, s57, s61
	s_cselect_b32 s66, s56, s55
	s_cselect_b32 s65, s59, s31
	s_cselect_b32 s64, s58, s9
	ds_read_b128 v[146:149], v154
	ds_read_b128 v[158:161], v154 offset:1024
	ds_read_b128 v[162:165], v154 offset:2048
	ds_read_b128 v[166:169], v154 offset:3072
	ds_read_b128 v[170:173], v155
	ds_read_b128 v[174:177], v155 offset:1024
	ds_read_b128 v[178:181], v155 offset:2048
	ds_read_b128 v[182:185], v155 offset:3072
	ds_read_b128 v[186:189], v155 offset:4096
	ds_read_b128 v[190:193], v155 offset:5120
	ds_read_b128 v[194:197], v155 offset:6144
	ds_read_b128 v[198:201], v155 offset:7168
	ds_read_b128 v[202:205], v156
	ds_read_b128 v[206:209], v156 offset:1024
	ds_read_b128 v[210:213], v156 offset:2048
	ds_read_b128 v[214:217], v156 offset:3072
	s_add_i32 m0, s68, 0xc000
	v_lshl_add_u64 v[242:243], s[62:63], 0, v[138:139]
	global_load_lds_dwordx4 v[242:243], off
	s_add_i32 m0, s68, 0xe000
	v_lshl_add_u64 v[242:243], s[62:63], 0, v[140:141]
	global_load_lds_dwordx4 v[242:243], off
	s_waitcnt vmcnt(8) lgkmcnt(0)
	s_barrier
	v_mfma_f32_16x16x32_bf16 v[124:127], v[146:149], v[170:173], v[124:127]
	v_mfma_f32_16x16x32_bf16 v[120:123], v[162:165], v[170:173], v[120:123]
	v_mfma_f32_16x16x32_bf16 v[108:111], v[146:149], v[178:181], v[108:111]
	v_mfma_f32_16x16x32_bf16 v[104:107], v[162:165], v[178:181], v[104:107]
	v_mfma_f32_16x16x32_bf16 v[92:95], v[146:149], v[186:189], v[92:95]
	v_mfma_f32_16x16x32_bf16 v[88:91], v[162:165], v[186:189], v[88:91]
	v_mfma_f32_16x16x32_bf16 v[76:79], v[146:149], v[194:197], v[76:79]
	v_mfma_f32_16x16x32_bf16 v[72:75], v[162:165], v[194:197], v[72:75]
	v_mfma_f32_16x16x32_bf16 v[124:127], v[158:161], v[174:177], v[124:127]
	v_mfma_f32_16x16x32_bf16 v[120:123], v[166:169], v[174:177], v[120:123]
	v_mfma_f32_16x16x32_bf16 v[108:111], v[158:161], v[182:185], v[108:111]
	v_mfma_f32_16x16x32_bf16 v[104:107], v[166:169], v[182:185], v[104:107]
	v_mfma_f32_16x16x32_bf16 v[92:95], v[158:161], v[190:193], v[92:95]
	v_mfma_f32_16x16x32_bf16 v[88:91], v[166:169], v[190:193], v[88:91]
	v_mfma_f32_16x16x32_bf16 v[76:79], v[158:161], v[198:201], v[76:79]
	v_mfma_f32_16x16x32_bf16 v[72:75], v[166:169], v[198:201], v[72:75]
	v_mfma_f32_16x16x32_bf16 v[116:119], v[202:205], v[170:173], v[116:119]
	v_mfma_f32_16x16x32_bf16 v[112:115], v[210:213], v[170:173], v[112:115]
	v_mfma_f32_16x16x32_bf16 v[100:103], v[202:205], v[178:181], v[100:103]
	v_mfma_f32_16x16x32_bf16 v[96:99], v[210:213], v[178:181], v[96:99]
	v_mfma_f32_16x16x32_bf16 v[84:87], v[202:205], v[186:189], v[84:87]
	v_mfma_f32_16x16x32_bf16 v[80:83], v[210:213], v[186:189], v[80:83]
	v_mfma_f32_16x16x32_bf16 v[68:71], v[202:205], v[194:197], v[68:71]
	v_mfma_f32_16x16x32_bf16 v[64:67], v[210:213], v[194:197], v[64:67]
	v_mfma_f32_16x16x32_bf16 v[116:119], v[206:209], v[174:177], v[116:119]
	v_mfma_f32_16x16x32_bf16 v[112:115], v[214:217], v[174:177], v[112:115]
	v_mfma_f32_16x16x32_bf16 v[100:103], v[206:209], v[182:185], v[100:103]
	v_mfma_f32_16x16x32_bf16 v[96:99], v[214:217], v[182:185], v[96:99]
	v_mfma_f32_16x16x32_bf16 v[84:87], v[206:209], v[190:193], v[84:87]
	v_mfma_f32_16x16x32_bf16 v[80:83], v[214:217], v[190:193], v[80:83]
	v_mfma_f32_16x16x32_bf16 v[68:71], v[206:209], v[198:201], v[68:71]
	v_mfma_f32_16x16x32_bf16 v[64:67], v[214:217], v[198:201], v[64:67]
	s_barrier
	ds_read_b128 v[170:173], v155 offset:16384
	ds_read_b128 v[174:177], v155 offset:17408
	ds_read_b128 v[178:181], v155 offset:18432
	ds_read_b128 v[182:185], v155 offset:19456
	ds_read_b128 v[186:189], v155 offset:20480
	ds_read_b128 v[190:193], v155 offset:21504
	ds_read_b128 v[194:197], v155 offset:22528
	ds_read_b128 v[198:201], v155 offset:23552
	s_add_i32 s55, s78, s35
	s_mov_b32 m0, s55
	v_lshl_add_u64 v[218:219], s[64:65], 0, v[132:133]
	global_load_lds_dwordx4 v[218:219], off
	s_add_i32 m0, s55, 0x2000
	v_lshl_add_u64 v[220:221], s[64:65], 0, v[136:137]
	global_load_lds_dwordx4 v[220:221], off
	s_mov_b32 m0, s68
	v_lshl_add_u64 v[222:223], s[66:67], 0, v[130:131]
	global_load_lds_dwordx4 v[222:223], off
	s_mov_b32 m0, s69
	v_lshl_add_u64 v[224:225], s[66:67], 0, v[134:135]
	global_load_lds_dwordx4 v[224:225], off
	s_add_u32 s82, s64, 0x40000
	s_addc_u32 s83, s65, 0
	s_add_i32 s55, s79, s35
	s_mov_b32 m0, s55
	v_lshl_add_u64 v[240:241], s[82:83], 0, v[132:133]
	global_load_lds_dwordx4 v[240:241], off
	s_add_i32 m0, s55, 0x2000
	v_lshl_add_u64 v[240:241], s[82:83], 0, v[136:137]
	global_load_lds_dwordx4 v[240:241], off
	s_waitcnt vmcnt(8) lgkmcnt(0)
	s_barrier
; #define PG8_STAGE(bufoff, gbase, voff) do { _Pragma("unroll") for (int _i = 0; _i < 2; ++_i) \
;         __builtin_amdgcn_global_load_lds((const unsigned*)((const char*)(gbase) + (voff)[_i]), (LAS unsigned*)(lds + (bufoff) + ldsw + _i * 8192), 16, 0, 0); } while (0)
; #define PG8_LDA(dst, b, h) do { _Pragma("unroll") for (int m = 0; m < 4; ++m) _Pragma("unroll") for (int k = 0; k < 2; ++k) dst[m][k] = *(const LAS bf16x8*)(lds + PG8_SA(b, h) + aoff + m * 2048 + k * 1024); } while (0)
; #define PG8_LDB(dst, b, h) do { _Pragma("unroll") for (int n = 0; n < 2; ++n) _Pragma("unroll") for (int k = 0; k < 2; ++k) dst[n][k] = *(const LAS bf16x8*)(lds + PG8_SB(b, h) + boff + n * 2048 + k * 1024); } while (0)
; #define PG8_MMA(ai, bj, At, Bt) do { __builtin_amdgcn_s_setprio(1); _Pragma("unroll") for (int m = 0; m < 4; ++m) _Pragma("unroll") for (int n = 0; n < 2; ++n) _Pragma("unroll") for (int k = 0; k < 2; ++k) \
;         acc[ai][bj][m][n] = __builtin_amdgcn_mfma_f32_16x16x32_bf16(Bt[n][k], At[m][k], acc[ai][bj][m][n], 0, 0, 0); __builtin_amdgcn_s_setprio(0); } while (0)
; #define PG8_WAIT_V(n) asm volatile("s_waitcnt vmcnt(" #n ")" ::: "memory")
; #define PG8_WAIT_L(n) asm volatile("s_waitcnt lgkmcnt(" #n ")" ::: "memory")
; #define PG8_BAR __builtin_amdgcn_s_barrier()
; #define PG8_SCHED __builtin_amdgcn_sched_barrier(0)
; template <class Epi>
; __device__ __forceinline__ void gemm_phase(LAS unsigned char* lds, const Gemm g, const StaticOrder& S, const Epi& E) {
;     ...
;             PG8_BAR; PG8_WAIT_L(0); PG8_MMA(1, 0, At, B0); PG8_BAR; PG8_SCHED;
;             PG8_STAGE(PG8_SB(0, 1), b2 + hstepB, voffB);
;             PG8_WAIT_V(6); PG8_BAR; PG8_MMA(1, 1, At, B1); PG8_BAR;
;             PG8_LDB(B0, 1, 0); PG8_SCHED; PG8_LDA(At, 1, 0); PG8_STAGE(PG8_SA(0, 1), a2 + hstepA, voffA);
;             PG8_WAIT_L(8); PG8_BAR; PG8_WAIT_L(0); PG8_MMA(0, 0, At, B0); PG8_BAR; PG8_SCHED;
;             PG8_LDB(B1, 1, 1); PG8_STAGE(PG8_SB(1, 0), b3, voffB);
;             PG8_BAR; PG8_WAIT_L(0); PG8_MMA(0, 1, At, B1); PG8_BAR;
;             PG8_LDA(At, 1, 1); PG8_STAGE(PG8_SA(1, 0), a3, voffA);
;             PG8_BAR; PG8_WAIT_L(0); PG8_MMA(1, 0, At, B0); PG8_BAR; PG8_SCHED;
;             PG8_STAGE(PG8_SB(1, 1), b3 + hstepB, voffB);
;             PG8_WAIT_V(6); PG8_BAR; PG8_MMA(1, 1, At, B1); PG8_BAR;
	v_mfma_f32_16x16x32_bf16 v[60:63], v[146:149], v[170:173], v[60:63]
	v_mfma_f32_16x16x32_bf16 v[56:59], v[162:165], v[170:173], v[56:59]
	v_mfma_f32_16x16x32_bf16 v[44:47], v[146:149], v[178:181], v[44:47]
	v_mfma_f32_16x16x32_bf16 v[40:43], v[162:165], v[178:181], v[40:43]
	v_mfma_f32_16x16x32_bf16 v[28:31], v[146:149], v[186:189], v[28:31]
	v_mfma_f32_16x16x32_bf16 v[24:27], v[162:165], v[186:189], v[24:27]
	v_mfma_f32_16x16x32_bf16 v[12:15], v[146:149], v[194:197], v[12:15]
	v_mfma_f32_16x16x32_bf16 v[8:11], v[162:165], v[194:197], v[8:11]
	v_mfma_f32_16x16x32_bf16 v[60:63], v[158:161], v[174:177], v[60:63]
	v_mfma_f32_16x16x32_bf16 v[56:59], v[166:169], v[174:177], v[56:59]
	v_mfma_f32_16x16x32_bf16 v[44:47], v[158:161], v[182:185], v[44:47]
	v_mfma_f32_16x16x32_bf16 v[40:43], v[166:169], v[182:185], v[40:43]
	v_mfma_f32_16x16x32_bf16 v[28:31], v[158:161], v[190:193], v[28:31]
	v_mfma_f32_16x16x32_bf16 v[24:27], v[166:169], v[190:193], v[24:27]
	v_mfma_f32_16x16x32_bf16 v[12:15], v[158:161], v[198:201], v[12:15]
	v_mfma_f32_16x16x32_bf16 v[8:11], v[166:169], v[198:201], v[8:11]
	v_mfma_f32_16x16x32_bf16 v[52:55], v[202:205], v[170:173], v[52:55]
	v_mfma_f32_16x16x32_bf16 v[48:51], v[210:213], v[170:173], v[48:51]
	v_mfma_f32_16x16x32_bf16 v[36:39], v[202:205], v[178:181], v[36:39]
	v_mfma_f32_16x16x32_bf16 v[32:35], v[210:213], v[178:181], v[32:35]
	v_mfma_f32_16x16x32_bf16 v[20:23], v[202:205], v[186:189], v[20:23]
	v_mfma_f32_16x16x32_bf16 v[16:19], v[210:213], v[186:189], v[16:19]
	v_mfma_f32_16x16x32_bf16 v[4:7], v[202:205], v[194:197], v[4:7]
	v_mfma_f32_16x16x32_bf16 v[0:3], v[210:213], v[194:197], v[0:3]
	v_mfma_f32_16x16x32_bf16 v[52:55], v[206:209], v[174:177], v[52:55]
	v_mfma_f32_16x16x32_bf16 v[48:51], v[214:217], v[174:177], v[48:51]
	v_mfma_f32_16x16x32_bf16 v[36:39], v[206:209], v[182:185], v[36:39]
	v_mfma_f32_16x16x32_bf16 v[32:35], v[214:217], v[182:185], v[32:35]
	v_mfma_f32_16x16x32_bf16 v[20:23], v[206:209], v[190:193], v[20:23]
	v_mfma_f32_16x16x32_bf16 v[16:19], v[214:217], v[190:193], v[16:19]
	v_mfma_f32_16x16x32_bf16 v[4:7], v[206:209], v[198:201], v[4:7]
	v_mfma_f32_16x16x32_bf16 v[0:3], v[214:217], v[198:201], v[0:3]
	s_barrier
	s_add_i32 s55, 0, 0x18000
	v_add_u32_e32 v157, s55, v152
	ds_read_b128 v[146:149], v157
	ds_read_b128 v[158:161], v157 offset:1024
	ds_read_b128 v[162:165], v157 offset:2048
	ds_read_b128 v[166:169], v157 offset:3072
	ds_read_b128 v[170:173], v155 offset:32768
	ds_read_b128 v[174:177], v155 offset:33792
	ds_read_b128 v[178:181], v155 offset:34816
	ds_read_b128 v[182:185], v155 offset:35840
	ds_read_b128 v[186:189], v155 offset:36864
	ds_read_b128 v[190:193], v155 offset:37888
	ds_read_b128 v[194:197], v155 offset:38912
	ds_read_b128 v[198:201], v155 offset:39936
	s_add_i32 s98, 0, 0x1c000
	v_add_u32_e32 v246, s98, v152
	ds_read_b128 v[202:205], v246
	ds_read_b128 v[206:209], v246 offset:1024
	ds_read_b128 v[210:213], v246 offset:2048
	ds_read_b128 v[214:217], v246 offset:3072
	s_add_u32 s66, s66, 0x40000
	s_addc_u32 s67, s67, 0
	s_mov_b32 m0, s70
	v_lshl_add_u64 v[244:245], s[66:67], 0, v[130:131]
	global_load_lds_dwordx4 v[244:245], off
	s_mov_b32 m0, s71
	v_lshl_add_u64 v[244:245], s[66:67], 0, v[134:135]
	global_load_lds_dwordx4 v[244:245], off
	s_waitcnt vmcnt(8) lgkmcnt(0)
	s_barrier
	v_mfma_f32_16x16x32_bf16 v[124:127], v[146:149], v[170:173], v[124:127]
	v_mfma_f32_16x16x32_bf16 v[120:123], v[162:165], v[170:173], v[120:123]
	v_mfma_f32_16x16x32_bf16 v[108:111], v[146:149], v[178:181], v[108:111]
	v_mfma_f32_16x16x32_bf16 v[104:107], v[162:165], v[178:181], v[104:107]
	v_mfma_f32_16x16x32_bf16 v[92:95], v[146:149], v[186:189], v[92:95]
	v_mfma_f32_16x16x32_bf16 v[88:91], v[162:165], v[186:189], v[88:91]
	v_mfma_f32_16x16x32_bf16 v[76:79], v[146:149], v[194:197], v[76:79]
	v_mfma_f32_16x16x32_bf16 v[72:75], v[162:165], v[194:197], v[72:75]
	v_mfma_f32_16x16x32_bf16 v[124:127], v[158:161], v[174:177], v[124:127]
	v_mfma_f32_16x16x32_bf16 v[120:123], v[166:169], v[174:177], v[120:123]
	v_mfma_f32_16x16x32_bf16 v[108:111], v[158:161], v[182:185], v[108:111]
	v_mfma_f32_16x16x32_bf16 v[104:107], v[166:169], v[182:185], v[104:107]
	v_mfma_f32_16x16x32_bf16 v[92:95], v[158:161], v[190:193], v[92:95]
	v_mfma_f32_16x16x32_bf16 v[88:91], v[166:169], v[190:193], v[88:91]
	v_mfma_f32_16x16x32_bf16 v[76:79], v[158:161], v[198:201], v[76:79]
	v_mfma_f32_16x16x32_bf16 v[72:75], v[166:169], v[198:201], v[72:75]
	v_mfma_f32_16x16x32_bf16 v[116:119], v[202:205], v[170:173], v[116:119]
	v_mfma_f32_16x16x32_bf16 v[112:115], v[210:213], v[170:173], v[112:115]
	v_mfma_f32_16x16x32_bf16 v[100:103], v[202:205], v[178:181], v[100:103]
	v_mfma_f32_16x16x32_bf16 v[96:99], v[210:213], v[178:181], v[96:99]
	v_mfma_f32_16x16x32_bf16 v[84:87], v[202:205], v[186:189], v[84:87]
	v_mfma_f32_16x16x32_bf16 v[80:83], v[210:213], v[186:189], v[80:83]
	v_mfma_f32_16x16x32_bf16 v[68:71], v[202:205], v[194:197], v[68:71]
	v_mfma_f32_16x16x32_bf16 v[64:67], v[210:213], v[194:197], v[64:67]
	v_mfma_f32_16x16x32_bf16 v[116:119], v[206:209], v[174:177], v[116:119]
	v_mfma_f32_16x16x32_bf16 v[112:115], v[214:217], v[174:177], v[112:115]
	v_mfma_f32_16x16x32_bf16 v[100:103], v[206:209], v[182:185], v[100:103]
	v_mfma_f32_16x16x32_bf16 v[96:99], v[214:217], v[182:185], v[96:99]
	v_mfma_f32_16x16x32_bf16 v[84:87], v[206:209], v[190:193], v[84:87]
	v_mfma_f32_16x16x32_bf16 v[80:83], v[214:217], v[190:193], v[80:83]
	v_mfma_f32_16x16x32_bf16 v[68:71], v[206:209], v[198:201], v[68:71]
	v_mfma_f32_16x16x32_bf16 v[64:67], v[214:217], v[198:201], v[64:67]
	s_barrier
; __device__ __forceinline__ unsigned pk2(float lo, float hi) { unsigned r; asm("v_cvt_pk_bf16_f32 %0, %1, %2" : "=v"(r) : "v"(lo), "v"(hi)); return r; }
; __device__ __forceinline__ float gelu_t(float x) { return x * __builtin_amdgcn_rcpf(1.f + __expf(-1.5957691216057308f * (x + 0.044715f * x * x * x))); }
; #define PG8_STAGE(bufoff, gbase, voff) do { _Pragma("unroll") for (int _i = 0; _i < 2; ++_i) \
;         __builtin_amdgcn_global_load_lds((const unsigned*)((const char*)(gbase) + (voff)[_i]), (LAS unsigned*)(lds + (bufoff) + ldsw + _i * 8192), 16, 0, 0); } while (0)
; #define PG8_LDA(dst, b, h) do { _Pragma("unroll") for (int m = 0; m < 4; ++m) _Pragma("unroll") for (int k = 0; k < 2; ++k) dst[m][k] = *(const LAS bf16x8*)(lds + PG8_SA(b, h) + aoff + m * 2048 + k * 1024); } while (0)
; #define PG8_MMA(ai, bj, At, Bt) do { __builtin_amdgcn_s_setprio(1); _Pragma("unroll") for (int m = 0; m < 4; ++m) _Pragma("unroll") for (int n = 0; n < 2; ++n) _Pragma("unroll") for (int k = 0; k < 2; ++k) \
;         acc[ai][bj][m][n] = __builtin_amdgcn_mfma_f32_16x16x32_bf16(Bt[n][k], At[m][k], acc[ai][bj][m][n], 0, 0, 0); __builtin_amdgcn_s_setprio(0); } while (0)
; #define PG8_WAIT_V(n) asm volatile("s_waitcnt vmcnt(" #n ")" ::: "memory")
; #define PG8_WAIT_L(n) asm volatile("s_waitcnt lgkmcnt(" #n ")" ::: "memory")
;     __device__ __forceinline__ void operator()(const f32x4 (&acc)[2][2][4][2], const Unit& u, int wr, int wc, int fr, int fq) const {
;     ...
;                 for (int bj = 0; bj < 2; ++bj) { f32x4 v0 = acc[ai][bj][m][0], v1 = acc[ai][bj][m][1];
;                     if (col0 + bj * HALF >= gelu_from) { v0 = (f32x4){gelu_t(v0.x), gelu_t(v0.y), gelu_t(v0.z), gelu_t(v0.w)}; v1 = (f32x4){gelu_t(v1.x), gelu_t(v1.y), gelu_t(v1.z), gelu_t(v1.w)}; }
;                     u32x4 w; w.x = pk2(v0[0], v0[1]); w.y = pk2(v0[2], v0[3]); w.z = pk2(v1[0], v1[1]); w.w = pk2(v1[2], v1[3]);
; template <class Epi>
; __device__ __forceinline__ void gemm_phase(LAS unsigned char* lds, const Gemm g, const StaticOrder& S, const Epi& E) {
;     ...
;             PG8_LDA(At, 1, 1); PG8_STAGE(PG8_SA(1, 0), a3, voffA);
;             PG8_BAR; PG8_WAIT_L(0); PG8_MMA(1, 0, At, B0); PG8_BAR; PG8_SCHED;
;             PG8_STAGE(PG8_SB(1, 1), b3 + hstepB, voffB);
;             PG8_WAIT_V(6); PG8_BAR; PG8_MMA(1, 1, At, B1); PG8_BAR;
;         }
;         E(acc, cur, wr, wc, fr, fq);
	ds_read_b128 v[170:173], v155 offset:49152
	ds_read_b128 v[174:177], v155 offset:50176
	ds_read_b128 v[178:181], v155 offset:51200
	ds_read_b128 v[182:185], v155 offset:52224
	ds_read_b128 v[186:189], v155 offset:53248
	ds_read_b128 v[190:193], v155 offset:54272
	ds_read_b128 v[194:197], v155 offset:55296
	ds_read_b128 v[198:201], v155 offset:56320
	s_add_i32 s55, s55, s35
	s_mov_b32 m0, s55
	v_lshl_add_u64 v[218:219], v[218:219], 0, s[28:29]
	global_load_lds_dwordx4 v[218:219], off
	s_add_i32 m0, s55, 0x2000
	v_lshl_add_u64 v[218:219], v[220:221], 0, s[28:29]
	global_load_lds_dwordx4 v[218:219], off
	s_mov_b32 m0, s73
	v_lshl_add_u64 v[218:219], v[222:223], 0, s[28:29]
	global_load_lds_dwordx4 v[218:219], off
	s_mov_b32 m0, s74
	v_lshl_add_u64 v[218:219], v[224:225], 0, s[28:29]
	global_load_lds_dwordx4 v[218:219], off
	s_add_u32 s64, s64, 0x40080
	s_addc_u32 s65, s65, 0
	s_add_i32 s55, s98, s35
	s_mov_b32 m0, s55
	v_lshl_add_u64 v[240:241], s[64:65], 0, v[132:133]
	global_load_lds_dwordx4 v[240:241], off
	s_add_i32 m0, s55, 0x2000
	v_lshl_add_u64 v[240:241], s[64:65], 0, v[136:137]
	global_load_lds_dwordx4 v[240:241], off
	s_waitcnt vmcnt(8) lgkmcnt(0)
	s_barrier
	v_mfma_f32_16x16x32_bf16 v[60:63], v[146:149], v[170:173], v[60:63]
	v_mfma_f32_16x16x32_bf16 v[56:59], v[162:165], v[170:173], v[56:59]
	v_mfma_f32_16x16x32_bf16 v[44:47], v[146:149], v[178:181], v[44:47]
	v_mfma_f32_16x16x32_bf16 v[40:43], v[162:165], v[178:181], v[40:43]
	v_mfma_f32_16x16x32_bf16 v[28:31], v[146:149], v[186:189], v[28:31]
	v_mfma_f32_16x16x32_bf16 v[24:27], v[162:165], v[186:189], v[24:27]
	v_mfma_f32_16x16x32_bf16 v[12:15], v[146:149], v[194:197], v[12:15]
	v_mfma_f32_16x16x32_bf16 v[8:11], v[162:165], v[194:197], v[8:11]
	v_mfma_f32_16x16x32_bf16 v[60:63], v[158:161], v[174:177], v[60:63]
	v_mfma_f32_16x16x32_bf16 v[56:59], v[166:169], v[174:177], v[56:59]
	v_mfma_f32_16x16x32_bf16 v[44:47], v[158:161], v[182:185], v[44:47]
	v_mfma_f32_16x16x32_bf16 v[40:43], v[166:169], v[182:185], v[40:43]
	v_mfma_f32_16x16x32_bf16 v[28:31], v[158:161], v[190:193], v[28:31]
	v_mfma_f32_16x16x32_bf16 v[24:27], v[166:169], v[190:193], v[24:27]
	v_mfma_f32_16x16x32_bf16 v[12:15], v[158:161], v[198:201], v[12:15]
	v_mfma_f32_16x16x32_bf16 v[8:11], v[166:169], v[198:201], v[8:11]
	v_mfma_f32_16x16x32_bf16 v[52:55], v[202:205], v[170:173], v[52:55]
	v_mfma_f32_16x16x32_bf16 v[48:51], v[210:213], v[170:173], v[48:51]
	v_mfma_f32_16x16x32_bf16 v[36:39], v[202:205], v[178:181], v[36:39]
	v_mfma_f32_16x16x32_bf16 v[32:35], v[210:213], v[178:181], v[32:35]
	v_mfma_f32_16x16x32_bf16 v[20:23], v[202:205], v[186:189], v[20:23]
	v_mfma_f32_16x16x32_bf16 v[16:19], v[210:213], v[186:189], v[16:19]
	v_mfma_f32_16x16x32_bf16 v[4:7], v[202:205], v[194:197], v[4:7]
	v_mfma_f32_16x16x32_bf16 v[0:3], v[210:213], v[194:197], v[0:3]
	v_mfma_f32_16x16x32_bf16 v[52:55], v[206:209], v[174:177], v[52:55]
	v_mfma_f32_16x16x32_bf16 v[48:51], v[214:217], v[174:177], v[48:51]
	v_mfma_f32_16x16x32_bf16 v[36:39], v[206:209], v[182:185], v[36:39]
	v_mfma_f32_16x16x32_bf16 v[32:35], v[214:217], v[182:185], v[32:35]
	v_mfma_f32_16x16x32_bf16 v[20:23], v[206:209], v[190:193], v[20:23]
	v_mfma_f32_16x16x32_bf16 v[16:19], v[214:217], v[190:193], v[16:19]
	v_mfma_f32_16x16x32_bf16 v[4:7], v[206:209], v[198:201], v[4:7]
	v_mfma_f32_16x16x32_bf16 v[0:3], v[214:217], v[198:201], v[0:3]
	s_add_i32 s33, s33, 2
	s_add_u32 s62, s62, 0x100
	s_addc_u32 s63, s63, 0
	s_add_u32 s9, s9, 0x100
	s_addc_u32 s31, s31, 0
	s_cmp_gt_u32 s33, 13
	s_cbranch_scc1 .Leo_exit0
	s_barrier
	s_branch .LBB0_119
.Leo_exit0:
	s_cmpk_gt_u32 s3, 0xff
	s_cbranch_scc1 .Leo_b0
	s_barrier
.Leo_b0:
	v_lshl_or_b32 v146, s60, 8, v153
	v_cmp_lt_i32_e32 vcc, s80, v146
	s_and_saveexec_b64 s[60:61], vcc
	s_cbranch_execz .LBB0_122
	v_mul_f32_e32 v148, 0x3d372713, v125
	v_mul_f32_e32 v148, v125, v148
	v_fma_f32 v148, v125, v148, v125
	v_mul_f32_e32 v147, 0x3d372713, v124
	v_mul_f32_e32 v148, 0xbfcc422a, v148
	v_mul_f32_e32 v147, v124, v147
	v_mul_f32_e32 v148, 0x3fb8aa3b, v148
	v_fma_f32 v147, v124, v147, v124
	v_exp_f32_e32 v149, v148
	v_mul_f32_e32 v148, 0x3d372713, v126
	v_mul_f32_e32 v147, 0xbfcc422a, v147
	v_mul_f32_e32 v148, v126, v148
	v_mul_f32_e32 v147, 0x3fb8aa3b, v147
	v_fma_f32 v148, v126, v148, v126
	v_exp_f32_e32 v147, v147
	v_mul_f32_e32 v148, 0xbfcc422a, v148
	v_mul_f32_e32 v148, 0x3fb8aa3b, v148
	v_exp_f32_e32 v157, v148
	v_add_f32_e32 v147, 1.0, v147
	v_rcp_f32_e32 v148, v147
	v_add_f32_e32 v147, 1.0, v149
	v_rcp_f32_e32 v149, v147
	v_add_f32_e32 v147, 1.0, v157
	v_mul_f32_e32 v157, 0x3d372713, v127
	v_mul_f32_e32 v157, v127, v157
	v_mul_f32_e32 v158, 0x3d372713, v120
	v_fma_f32 v157, v127, v157, v127
	v_mul_f32_e32 v158, v120, v158
	v_mul_f32_e32 v157, 0xbfcc422a, v157
	v_fma_f32 v158, v120, v158, v120
	v_mul_f32_e32 v157, 0x3fb8aa3b, v157
	v_mul_f32_e32 v158, 0xbfcc422a, v158
	v_exp_f32_e32 v157, v157
	v_mul_f32_e32 v158, 0x3fb8aa3b, v158
	v_exp_f32_e32 v160, v158
	v_rcp_f32_e32 v158, v147
	v_add_f32_e32 v147, 1.0, v157
	v_rcp_f32_e32 v159, v147
	v_add_f32_e32 v147, 1.0, v160
	v_mul_f32_e32 v157, 0x3d372713, v122
	v_rcp_f32_e32 v160, v147
	v_mul_f32_e32 v147, 0x3d372713, v121
	v_mul_f32_e32 v157, v122, v157
	v_mul_f32_e32 v161, 0x3d372713, v123
	v_mul_f32_e32 v147, v121, v147
	v_fma_f32 v157, v122, v157, v122
	v_mul_f32_e32 v161, v123, v161
	v_fma_f32 v147, v121, v147, v121
	v_mul_f32_e32 v157, 0xbfcc422a, v157
	v_fma_f32 v161, v123, v161, v123
	v_mul_f32_e32 v147, 0xbfcc422a, v147
	v_mul_f32_e32 v157, 0x3fb8aa3b, v157
	v_mul_f32_e32 v161, 0xbfcc422a, v161
	v_mul_f32_e32 v147, 0x3fb8aa3b, v147
	v_exp_f32_e32 v157, v157
	v_mul_f32_e32 v161, 0x3fb8aa3b, v161
	v_exp_f32_e32 v147, v147
	v_exp_f32_e32 v161, v161
	v_add_f32_e32 v157, 1.0, v157
	v_rcp_f32_e32 v162, v157
	v_add_f32_e32 v147, 1.0, v147
	v_add_f32_e32 v157, 1.0, v161
	v_rcp_f32_e32 v163, v157
	v_rcp_f32_e32 v161, v147
	v_pk_mul_f32 v[126:127], v[126:127], v[158:159]
	v_pk_mul_f32 v[124:125], v[124:125], v[148:149]
	v_pk_mul_f32 v[122:123], v[122:123], v[162:163]
	v_pk_mul_f32 v[120:121], v[120:121], v[160:161]

; template <class Epi>
; __device__ __forceinline__ void gemm_phase(LAS unsigned char* lds, const Gemm g, const StaticOrder& S, const Epi& E) {
;     ...
;     for (;;) {
;         const bool has_next = S.next(ui + 1, nxt);
.LBB0_441:
	s_cmpk_gt_u32 s3, 0xff
	s_cbranch_scc0 .Leo_l1
	s_barrier

; #define PG8_STAGE(bufoff, gbase, voff) do { _Pragma("unroll") for (int _i = 0; _i < 2; ++_i) \
;         __builtin_amdgcn_global_load_lds((const unsigned*)((const char*)(gbase) + (voff)[_i]), (LAS unsigned*)(lds + (bufoff) + ldsw + _i * 8192), 16, 0, 0); } while (0)
; #define PG8_LDA(dst, b, h) do { _Pragma("unroll") for (int m = 0; m < 4; ++m) _Pragma("unroll") for (int k = 0; k < 2; ++k) dst[m][k] = *(const LAS bf16x8*)(lds + PG8_SA(b, h) + aoff + m * 2048 + k * 1024); } while (0)
; #define PG8_LDB(dst, b, h) do { _Pragma("unroll") for (int n = 0; n < 2; ++n) _Pragma("unroll") for (int k = 0; k < 2; ++k) dst[n][k] = *(const LAS bf16x8*)(lds + PG8_SB(b, h) + boff + n * 2048 + k * 1024); } while (0)
; #define PG8_MMA(ai, bj, At, Bt) do { __builtin_amdgcn_s_setprio(1); _Pragma("unroll") for (int m = 0; m < 4; ++m) _Pragma("unroll") for (int n = 0; n < 2; ++n) _Pragma("unroll") for (int k = 0; k < 2; ++k) \
;         acc[ai][bj][m][n] = __builtin_amdgcn_mfma_f32_16x16x32_bf16(Bt[n][k], At[m][k], acc[ai][bj][m][n], 0, 0, 0); __builtin_amdgcn_s_setprio(0); } while (0)
; #define PG8_WAIT_V(n) asm volatile("s_waitcnt vmcnt(" #n ")" ::: "memory")
; #define PG8_WAIT_L(n) asm volatile("s_waitcnt lgkmcnt(" #n ")" ::: "memory")
; template <class Epi>
; __device__ __forceinline__ void gemm_phase(LAS unsigned char* lds, const Gemm g, const StaticOrder& S, const Epi& E) {
;     ...
;         for (int t = 0; t < nt; t += 2) {
;             const bool last = (t == nt - 2);
;             const char* a1 = cA + (size_t)(t + 1) * kstep;
;             const char* a2 = last ? nA : cA + (size_t)(t + 2) * kstep; const char* b2 = last ? nB : cB + (size_t)(t + 2) * kstep;
;             const char* a3 = a2 + kstep; const char* b3 = b2 + kstep;
;             PG8_LDB(B0, 0, 0); PG8_SCHED; PG8_LDA(At, 0, 0); PG8_STAGE(PG8_SA(1, 1), a1 + hstepA, voffA);
;             PG8_WAIT_L(8); PG8_BAR; PG8_WAIT_L(0); PG8_MMA(0, 0, At, B0); PG8_BAR; PG8_SCHED;
;             PG8_LDB(B1, 0, 1); PG8_STAGE(PG8_SB(0, 0), b2, voffB);
;             PG8_BAR; PG8_WAIT_L(0); PG8_MMA(0, 1, At, B1); PG8_BAR;
;             PG8_LDA(At, 0, 1); PG8_STAGE(PG8_SA(0, 0), a2, voffA);
;             PG8_BAR; PG8_WAIT_L(0); PG8_MMA(1, 0, At, B0); PG8_BAR; PG8_SCHED;
;             PG8_STAGE(PG8_SB(0, 1), b2 + hstepB, voffB);
;             PG8_WAIT_V(6); PG8_BAR; PG8_MMA(1, 1, At, B1); PG8_BAR;
.LBB0_456:
	s_add_i32 s85, s59, 2
	s_add_u32 s66, s64, 0xfffc0080
	s_addc_u32 s67, s65, -1
	s_cmp_eq_u32 s21, s59
	s_cselect_b32 s69, s63, s67
	s_cselect_b32 s68, s62, s66
	s_cselect_b32 s67, s1, s57
	s_cselect_b32 s66, s0, s31
	ds_read_b128 v[144:147], v158
	ds_read_b128 v[148:151], v158 offset:1024
	ds_read_b128 v[162:165], v158 offset:2048
	ds_read_b128 v[166:169], v158 offset:3072
	ds_read_b128 v[170:173], v159
	ds_read_b128 v[174:177], v159 offset:1024
	ds_read_b128 v[178:181], v159 offset:2048
	ds_read_b128 v[182:185], v159 offset:3072
	ds_read_b128 v[186:189], v159 offset:4096
	ds_read_b128 v[190:193], v159 offset:5120
	ds_read_b128 v[194:197], v159 offset:6144
	ds_read_b128 v[198:201], v159 offset:7168
	ds_read_b128 v[202:205], v160
	ds_read_b128 v[206:209], v160 offset:1024
	ds_read_b128 v[210:213], v160 offset:2048
	ds_read_b128 v[214:217], v160 offset:3072
	s_add_i32 m0, s35, 0xc000
	v_lshl_add_u64 v[152:153], s[64:65], 0, v[138:139]
	global_load_lds_dwordx4 v[152:153], off
	s_add_i32 m0, s35, 0xe000
	v_lshl_add_u64 v[152:153], s[64:65], 0, v[140:141]
	global_load_lds_dwordx4 v[152:153], off
	s_waitcnt vmcnt(8) lgkmcnt(0)
	s_barrier
	v_mfma_f32_16x16x32_bf16 v[124:127], v[144:147], v[170:173], v[124:127]
	v_mfma_f32_16x16x32_bf16 v[120:123], v[162:165], v[170:173], v[120:123]
	v_mfma_f32_16x16x32_bf16 v[116:119], v[144:147], v[178:181], v[116:119]
	v_mfma_f32_16x16x32_bf16 v[108:111], v[162:165], v[178:181], v[108:111]
	v_mfma_f32_16x16x32_bf16 v[100:103], v[144:147], v[186:189], v[100:103]
	v_mfma_f32_16x16x32_bf16 v[92:95], v[162:165], v[186:189], v[92:95]
	v_mfma_f32_16x16x32_bf16 v[84:87], v[144:147], v[194:197], v[84:87]
	v_mfma_f32_16x16x32_bf16 v[76:79], v[162:165], v[194:197], v[76:79]
	v_mfma_f32_16x16x32_bf16 v[124:127], v[148:151], v[174:177], v[124:127]
	v_mfma_f32_16x16x32_bf16 v[120:123], v[166:169], v[174:177], v[120:123]
	v_mfma_f32_16x16x32_bf16 v[116:119], v[148:151], v[182:185], v[116:119]
	v_mfma_f32_16x16x32_bf16 v[108:111], v[166:169], v[182:185], v[108:111]
	v_mfma_f32_16x16x32_bf16 v[100:103], v[148:151], v[190:193], v[100:103]
	v_mfma_f32_16x16x32_bf16 v[92:95], v[166:169], v[190:193], v[92:95]
	v_mfma_f32_16x16x32_bf16 v[84:87], v[148:151], v[198:201], v[84:87]
	v_mfma_f32_16x16x32_bf16 v[76:79], v[166:169], v[198:201], v[76:79]
	v_mfma_f32_16x16x32_bf16 v[112:115], v[202:205], v[170:173], v[112:115]
	v_mfma_f32_16x16x32_bf16 v[104:107], v[210:213], v[170:173], v[104:107]
	v_mfma_f32_16x16x32_bf16 v[96:99], v[202:205], v[178:181], v[96:99]
	v_mfma_f32_16x16x32_bf16 v[88:91], v[210:213], v[178:181], v[88:91]
	v_mfma_f32_16x16x32_bf16 v[80:83], v[202:205], v[186:189], v[80:83]
	v_mfma_f32_16x16x32_bf16 v[72:75], v[210:213], v[186:189], v[72:75]
	v_mfma_f32_16x16x32_bf16 v[68:71], v[202:205], v[194:197], v[68:71]
	v_mfma_f32_16x16x32_bf16 v[64:67], v[210:213], v[194:197], v[64:67]
	v_mfma_f32_16x16x32_bf16 v[112:115], v[206:209], v[174:177], v[112:115]
	v_mfma_f32_16x16x32_bf16 v[104:107], v[214:217], v[174:177], v[104:107]
	v_mfma_f32_16x16x32_bf16 v[96:99], v[206:209], v[182:185], v[96:99]
	v_mfma_f32_16x16x32_bf16 v[88:91], v[214:217], v[182:185], v[88:91]
	v_mfma_f32_16x16x32_bf16 v[80:83], v[206:209], v[190:193], v[80:83]
	v_mfma_f32_16x16x32_bf16 v[72:75], v[214:217], v[190:193], v[72:75]
	v_mfma_f32_16x16x32_bf16 v[68:71], v[206:209], v[198:201], v[68:71]
	v_mfma_f32_16x16x32_bf16 v[64:67], v[214:217], v[198:201], v[64:67]
	s_barrier
	ds_read_b128 v[170:173], v159 offset:16384
	ds_read_b128 v[174:177], v159 offset:17408
	ds_read_b128 v[178:181], v159 offset:18432
	ds_read_b128 v[182:185], v159 offset:19456
	ds_read_b128 v[186:189], v159 offset:20480
	ds_read_b128 v[190:193], v159 offset:21504
	ds_read_b128 v[194:197], v159 offset:22528
	ds_read_b128 v[198:201], v159 offset:23552
	s_add_i32 s59, s78, s33
	s_mov_b32 m0, s59
	v_lshl_add_u64 v[152:153], s[66:67], 0, v[132:133]
	global_load_lds_dwordx4 v[152:153], off
	s_add_i32 m0, s59, 0x2000
	v_lshl_add_u64 v[218:219], s[66:67], 0, v[136:137]
	global_load_lds_dwordx4 v[218:219], off
	s_mov_b32 m0, s35
	v_lshl_add_u64 v[220:221], s[68:69], 0, v[130:131]
	global_load_lds_dwordx4 v[220:221], off
	s_mov_b32 m0, s70
	v_lshl_add_u64 v[222:223], s[68:69], 0, v[134:135]
	global_load_lds_dwordx4 v[222:223], off
	s_add_u32 s86, s66, 0x40000
	s_addc_u32 s87, s67, 0
	s_add_i32 s59, s79, s33
	s_mov_b32 m0, s59
	v_lshl_add_u64 v[240:241], s[86:87], 0, v[132:133]
	global_load_lds_dwordx4 v[240:241], off
	s_add_i32 m0, s59, 0x2000
	v_lshl_add_u64 v[240:241], s[86:87], 0, v[136:137]
	global_load_lds_dwordx4 v[240:241], off
	s_waitcnt vmcnt(8) lgkmcnt(0)
	s_barrier
; #define PG8_STAGE(bufoff, gbase, voff) do { _Pragma("unroll") for (int _i = 0; _i < 2; ++_i) \
;         __builtin_amdgcn_global_load_lds((const unsigned*)((const char*)(gbase) + (voff)[_i]), (LAS unsigned*)(lds + (bufoff) + ldsw + _i * 8192), 16, 0, 0); } while (0)
; #define PG8_LDA(dst, b, h) do { _Pragma("unroll") for (int m = 0; m < 4; ++m) _Pragma("unroll") for (int k = 0; k < 2; ++k) dst[m][k] = *(const LAS bf16x8*)(lds + PG8_SA(b, h) + aoff + m * 2048 + k * 1024); } while (0)
; #define PG8_LDB(dst, b, h) do { _Pragma("unroll") for (int n = 0; n < 2; ++n) _Pragma("unroll") for (int k = 0; k < 2; ++k) dst[n][k] = *(const LAS bf16x8*)(lds + PG8_SB(b, h) + boff + n * 2048 + k * 1024); } while (0)
; #define PG8_MMA(ai, bj, At, Bt) do { __builtin_amdgcn_s_setprio(1); _Pragma("unroll") for (int m = 0; m < 4; ++m) _Pragma("unroll") for (int n = 0; n < 2; ++n) _Pragma("unroll") for (int k = 0; k < 2; ++k) \
;         acc[ai][bj][m][n] = __builtin_amdgcn_mfma_f32_16x16x32_bf16(Bt[n][k], At[m][k], acc[ai][bj][m][n], 0, 0, 0); __builtin_amdgcn_s_setprio(0); } while (0)
; #define PG8_WAIT_V(n) asm volatile("s_waitcnt vmcnt(" #n ")" ::: "memory")
; #define PG8_WAIT_L(n) asm volatile("s_waitcnt lgkmcnt(" #n ")" ::: "memory")
; #define PG8_BAR __builtin_amdgcn_s_barrier()
; #define PG8_SCHED __builtin_amdgcn_sched_barrier(0)
; template <class Epi>
; __device__ __forceinline__ void gemm_phase(LAS unsigned char* lds, const Gemm g, const StaticOrder& S, const Epi& E) {
;     ...
;             PG8_WAIT_V(6); PG8_BAR; PG8_MMA(1, 1, At, B1); PG8_BAR;
;             PG8_LDB(B0, 1, 0); PG8_SCHED; PG8_LDA(At, 1, 0); PG8_STAGE(PG8_SA(0, 1), a2 + hstepA, voffA);
;             PG8_WAIT_L(8); PG8_BAR; PG8_WAIT_L(0); PG8_MMA(0, 0, At, B0); PG8_BAR; PG8_SCHED;
;             PG8_LDB(B1, 1, 1); PG8_STAGE(PG8_SB(1, 0), b3, voffB);
;             PG8_BAR; PG8_WAIT_L(0); PG8_MMA(0, 1, At, B1); PG8_BAR;
;             PG8_LDA(At, 1, 1); PG8_STAGE(PG8_SA(1, 0), a3, voffA);
;             PG8_BAR; PG8_WAIT_L(0); PG8_MMA(1, 0, At, B0); PG8_BAR; PG8_SCHED;
	v_mfma_f32_16x16x32_bf16 v[60:63], v[144:147], v[170:173], v[60:63]
	v_mfma_f32_16x16x32_bf16 v[56:59], v[162:165], v[170:173], v[56:59]
	v_mfma_f32_16x16x32_bf16 v[52:55], v[144:147], v[178:181], v[52:55]
	v_mfma_f32_16x16x32_bf16 v[44:47], v[162:165], v[178:181], v[44:47]
	v_mfma_f32_16x16x32_bf16 v[36:39], v[144:147], v[186:189], v[36:39]
	v_mfma_f32_16x16x32_bf16 v[28:31], v[162:165], v[186:189], v[28:31]
	v_mfma_f32_16x16x32_bf16 v[20:23], v[144:147], v[194:197], v[20:23]
	v_mfma_f32_16x16x32_bf16 v[12:15], v[162:165], v[194:197], v[12:15]
	v_mfma_f32_16x16x32_bf16 v[60:63], v[148:151], v[174:177], v[60:63]
	v_mfma_f32_16x16x32_bf16 v[56:59], v[166:169], v[174:177], v[56:59]
	v_mfma_f32_16x16x32_bf16 v[52:55], v[148:151], v[182:185], v[52:55]
	v_mfma_f32_16x16x32_bf16 v[44:47], v[166:169], v[182:185], v[44:47]
	v_mfma_f32_16x16x32_bf16 v[36:39], v[148:151], v[190:193], v[36:39]
	v_mfma_f32_16x16x32_bf16 v[28:31], v[166:169], v[190:193], v[28:31]
	v_mfma_f32_16x16x32_bf16 v[20:23], v[148:151], v[198:201], v[20:23]
	v_mfma_f32_16x16x32_bf16 v[12:15], v[166:169], v[198:201], v[12:15]
	v_mfma_f32_16x16x32_bf16 v[48:51], v[202:205], v[170:173], v[48:51]
	v_mfma_f32_16x16x32_bf16 v[40:43], v[210:213], v[170:173], v[40:43]
	v_mfma_f32_16x16x32_bf16 v[32:35], v[202:205], v[178:181], v[32:35]
	v_mfma_f32_16x16x32_bf16 v[24:27], v[210:213], v[178:181], v[24:27]
	v_mfma_f32_16x16x32_bf16 v[16:19], v[202:205], v[186:189], v[16:19]
	v_mfma_f32_16x16x32_bf16 v[8:11], v[210:213], v[186:189], v[8:11]
	v_mfma_f32_16x16x32_bf16 v[4:7], v[202:205], v[194:197], v[4:7]
	v_mfma_f32_16x16x32_bf16 v[0:3], v[210:213], v[194:197], v[0:3]
	v_mfma_f32_16x16x32_bf16 v[48:51], v[206:209], v[174:177], v[48:51]
	v_mfma_f32_16x16x32_bf16 v[40:43], v[214:217], v[174:177], v[40:43]
	v_mfma_f32_16x16x32_bf16 v[32:35], v[206:209], v[182:185], v[32:35]
	v_mfma_f32_16x16x32_bf16 v[24:27], v[214:217], v[182:185], v[24:27]
	v_mfma_f32_16x16x32_bf16 v[16:19], v[206:209], v[190:193], v[16:19]
	v_mfma_f32_16x16x32_bf16 v[8:11], v[214:217], v[190:193], v[8:11]
	v_mfma_f32_16x16x32_bf16 v[4:7], v[206:209], v[198:201], v[4:7]
	v_mfma_f32_16x16x32_bf16 v[0:3], v[214:217], v[198:201], v[0:3]
	s_barrier
	s_add_i32 s59, 0, 0x18000
	v_add_u32_e32 v161, s59, v156
	ds_read_b128 v[144:147], v161
	ds_read_b128 v[148:151], v161 offset:1024
	ds_read_b128 v[162:165], v161 offset:2048
	ds_read_b128 v[166:169], v161 offset:3072
	ds_read_b128 v[170:173], v159 offset:32768
	ds_read_b128 v[174:177], v159 offset:33792
	ds_read_b128 v[178:181], v159 offset:34816
	ds_read_b128 v[182:185], v159 offset:35840
	ds_read_b128 v[186:189], v159 offset:36864
	ds_read_b128 v[190:193], v159 offset:37888
	ds_read_b128 v[194:197], v159 offset:38912
	ds_read_b128 v[198:201], v159 offset:39936
	s_add_i32 s98, 0, 0x1c000
	v_add_u32_e32 v246, s98, v156
	ds_read_b128 v[202:205], v246
	ds_read_b128 v[206:209], v246 offset:1024
	ds_read_b128 v[210:213], v246 offset:2048
	ds_read_b128 v[214:217], v246 offset:3072
	s_add_u32 s68, s68, 0x40000
	s_addc_u32 s69, s69, 0
	s_mov_b32 m0, s71
	v_lshl_add_u64 v[244:245], s[68:69], 0, v[130:131]
	global_load_lds_dwordx4 v[244:245], off
	s_mov_b32 m0, s72
	v_lshl_add_u64 v[244:245], s[68:69], 0, v[134:135]
	global_load_lds_dwordx4 v[244:245], off
	s_waitcnt vmcnt(8) lgkmcnt(0)
	s_barrier
	v_mfma_f32_16x16x32_bf16 v[124:127], v[144:147], v[170:173], v[124:127]
	v_mfma_f32_16x16x32_bf16 v[120:123], v[162:165], v[170:173], v[120:123]
	v_mfma_f32_16x16x32_bf16 v[116:119], v[144:147], v[178:181], v[116:119]
	v_mfma_f32_16x16x32_bf16 v[108:111], v[162:165], v[178:181], v[108:111]
	v_mfma_f32_16x16x32_bf16 v[100:103], v[144:147], v[186:189], v[100:103]
	v_mfma_f32_16x16x32_bf16 v[92:95], v[162:165], v[186:189], v[92:95]
	v_mfma_f32_16x16x32_bf16 v[84:87], v[144:147], v[194:197], v[84:87]
	v_mfma_f32_16x16x32_bf16 v[76:79], v[162:165], v[194:197], v[76:79]
	v_mfma_f32_16x16x32_bf16 v[124:127], v[148:151], v[174:177], v[124:127]
	v_mfma_f32_16x16x32_bf16 v[120:123], v[166:169], v[174:177], v[120:123]
	v_mfma_f32_16x16x32_bf16 v[116:119], v[148:151], v[182:185], v[116:119]
	v_mfma_f32_16x16x32_bf16 v[108:111], v[166:169], v[182:185], v[108:111]
	v_mfma_f32_16x16x32_bf16 v[100:103], v[148:151], v[190:193], v[100:103]
	v_mfma_f32_16x16x32_bf16 v[92:95], v[166:169], v[190:193], v[92:95]
	v_mfma_f32_16x16x32_bf16 v[84:87], v[148:151], v[198:201], v[84:87]
	v_mfma_f32_16x16x32_bf16 v[76:79], v[166:169], v[198:201], v[76:79]
	v_mfma_f32_16x16x32_bf16 v[112:115], v[202:205], v[170:173], v[112:115]
	v_mfma_f32_16x16x32_bf16 v[104:107], v[210:213], v[170:173], v[104:107]
	v_mfma_f32_16x16x32_bf16 v[96:99], v[202:205], v[178:181], v[96:99]
	v_mfma_f32_16x16x32_bf16 v[88:91], v[210:213], v[178:181], v[88:91]
	v_mfma_f32_16x16x32_bf16 v[80:83], v[202:205], v[186:189], v[80:83]
	v_mfma_f32_16x16x32_bf16 v[72:75], v[210:213], v[186:189], v[72:75]
	v_mfma_f32_16x16x32_bf16 v[68:71], v[202:205], v[194:197], v[68:71]
	v_mfma_f32_16x16x32_bf16 v[64:67], v[210:213], v[194:197], v[64:67]
	v_mfma_f32_16x16x32_bf16 v[112:115], v[206:209], v[174:177], v[112:115]
	v_mfma_f32_16x16x32_bf16 v[104:107], v[214:217], v[174:177], v[104:107]
	v_mfma_f32_16x16x32_bf16 v[96:99], v[206:209], v[182:185], v[96:99]
	v_mfma_f32_16x16x32_bf16 v[88:91], v[214:217], v[182:185], v[88:91]
	v_mfma_f32_16x16x32_bf16 v[80:83], v[206:209], v[190:193], v[80:83]
	v_mfma_f32_16x16x32_bf16 v[72:75], v[214:217], v[190:193], v[72:75]
	v_mfma_f32_16x16x32_bf16 v[68:71], v[206:209], v[198:201], v[68:71]
	v_mfma_f32_16x16x32_bf16 v[64:67], v[214:217], v[198:201], v[64:67]
	s_barrier
; #define PG8_STAGE(bufoff, gbase, voff) do { _Pragma("unroll") for (int _i = 0; _i < 2; ++_i) \
;         __builtin_amdgcn_global_load_lds((const unsigned*)((const char*)(gbase) + (voff)[_i]), (LAS unsigned*)(lds + (bufoff) + ldsw + _i * 8192), 16, 0, 0); } while (0)
; #define PG8_LDA(dst, b, h) do { _Pragma("unroll") for (int m = 0; m < 4; ++m) _Pragma("unroll") for (int k = 0; k < 2; ++k) dst[m][k] = *(const LAS bf16x8*)(lds + PG8_SA(b, h) + aoff + m * 2048 + k * 1024); } while (0)
; #define PG8_MMA(ai, bj, At, Bt) do { __builtin_amdgcn_s_setprio(1); _Pragma("unroll") for (int m = 0; m < 4; ++m) _Pragma("unroll") for (int n = 0; n < 2; ++n) _Pragma("unroll") for (int k = 0; k < 2; ++k) \
;         acc[ai][bj][m][n] = __builtin_amdgcn_mfma_f32_16x16x32_bf16(Bt[n][k], At[m][k], acc[ai][bj][m][n], 0, 0, 0); __builtin_amdgcn_s_setprio(0); } while (0)
; #define PG8_WAIT_V(n) asm volatile("s_waitcnt vmcnt(" #n ")" ::: "memory")
; #define PG8_WAIT_L(n) asm volatile("s_waitcnt lgkmcnt(" #n ")" ::: "memory")
; #define PG8_BAR __builtin_amdgcn_s_barrier()
; #define PG8_SCHED __builtin_amdgcn_sched_barrier(0)
; template <class Epi>
; __device__ __forceinline__ void gemm_phase(LAS unsigned char* lds, const Gemm g, const StaticOrder& S, const Epi& E) {
;     ...
;             PG8_LDA(At, 1, 1); PG8_STAGE(PG8_SA(1, 0), a3, voffA);
;             PG8_BAR; PG8_WAIT_L(0); PG8_MMA(1, 0, At, B0); PG8_BAR; PG8_SCHED;
;             PG8_STAGE(PG8_SB(1, 1), b3 + hstepB, voffB);
;             PG8_WAIT_V(6); PG8_BAR; PG8_MMA(1, 1, At, B1); PG8_BAR;
;         }
	ds_read_b128 v[170:173], v159 offset:49152
	ds_read_b128 v[174:177], v159 offset:50176
	ds_read_b128 v[178:181], v159 offset:51200
	ds_read_b128 v[182:185], v159 offset:52224
	ds_read_b128 v[186:189], v159 offset:53248
	ds_read_b128 v[190:193], v159 offset:54272
	ds_read_b128 v[194:197], v159 offset:55296
	ds_read_b128 v[198:201], v159 offset:56320
	s_add_i32 s59, s59, s33
	s_mov_b32 m0, s59
	v_lshl_add_u64 v[152:153], v[152:153], 0, s[12:13]
	global_load_lds_dwordx4 v[152:153], off
	s_add_i32 m0, s59, 0x2000
	v_lshl_add_u64 v[152:153], v[218:219], 0, s[12:13]
	global_load_lds_dwordx4 v[152:153], off
	s_mov_b32 m0, s73
	v_lshl_add_u64 v[152:153], v[220:221], 0, s[12:13]
	global_load_lds_dwordx4 v[152:153], off
	s_mov_b32 m0, s74
	v_lshl_add_u64 v[152:153], v[222:223], 0, s[12:13]
	global_load_lds_dwordx4 v[152:153], off
	s_add_u32 s66, s66, 0x40080
	s_addc_u32 s67, s67, 0
	s_add_i32 s59, s98, s33
	s_mov_b32 m0, s59
	v_lshl_add_u64 v[240:241], s[66:67], 0, v[132:133]
	global_load_lds_dwordx4 v[240:241], off
	s_add_i32 m0, s59, 0x2000
	v_lshl_add_u64 v[240:241], s[66:67], 0, v[136:137]
	global_load_lds_dwordx4 v[240:241], off
	s_waitcnt vmcnt(8) lgkmcnt(0)
	s_barrier
	v_mfma_f32_16x16x32_bf16 v[60:63], v[144:147], v[170:173], v[60:63]
	v_mfma_f32_16x16x32_bf16 v[56:59], v[162:165], v[170:173], v[56:59]
	v_mfma_f32_16x16x32_bf16 v[52:55], v[144:147], v[178:181], v[52:55]
	v_mfma_f32_16x16x32_bf16 v[44:47], v[162:165], v[178:181], v[44:47]
	v_mfma_f32_16x16x32_bf16 v[36:39], v[144:147], v[186:189], v[36:39]
	v_mfma_f32_16x16x32_bf16 v[28:31], v[162:165], v[186:189], v[28:31]
	v_mfma_f32_16x16x32_bf16 v[20:23], v[144:147], v[194:197], v[20:23]
	v_mfma_f32_16x16x32_bf16 v[12:15], v[162:165], v[194:197], v[12:15]
	v_mfma_f32_16x16x32_bf16 v[60:63], v[148:151], v[174:177], v[60:63]
	v_mfma_f32_16x16x32_bf16 v[56:59], v[166:169], v[174:177], v[56:59]
	v_mfma_f32_16x16x32_bf16 v[52:55], v[148:151], v[182:185], v[52:55]
	v_mfma_f32_16x16x32_bf16 v[44:47], v[166:169], v[182:185], v[44:47]
	v_mfma_f32_16x16x32_bf16 v[36:39], v[148:151], v[190:193], v[36:39]
	v_mfma_f32_16x16x32_bf16 v[28:31], v[166:169], v[190:193], v[28:31]
	v_mfma_f32_16x16x32_bf16 v[20:23], v[148:151], v[198:201], v[20:23]
	v_mfma_f32_16x16x32_bf16 v[12:15], v[166:169], v[198:201], v[12:15]
	v_mfma_f32_16x16x32_bf16 v[48:51], v[202:205], v[170:173], v[48:51]
	v_mfma_f32_16x16x32_bf16 v[40:43], v[210:213], v[170:173], v[40:43]
	v_mfma_f32_16x16x32_bf16 v[32:35], v[202:205], v[178:181], v[32:35]
	v_mfma_f32_16x16x32_bf16 v[24:27], v[210:213], v[178:181], v[24:27]
	v_mfma_f32_16x16x32_bf16 v[16:19], v[202:205], v[186:189], v[16:19]
	v_mfma_f32_16x16x32_bf16 v[8:11], v[210:213], v[186:189], v[8:11]
	v_mfma_f32_16x16x32_bf16 v[4:7], v[202:205], v[194:197], v[4:7]
	v_mfma_f32_16x16x32_bf16 v[0:3], v[210:213], v[194:197], v[0:3]
	v_mfma_f32_16x16x32_bf16 v[48:51], v[206:209], v[174:177], v[48:51]
	v_mfma_f32_16x16x32_bf16 v[40:43], v[214:217], v[174:177], v[40:43]
	v_mfma_f32_16x16x32_bf16 v[32:35], v[206:209], v[182:185], v[32:35]
	v_mfma_f32_16x16x32_bf16 v[24:27], v[214:217], v[182:185], v[24:27]
	v_mfma_f32_16x16x32_bf16 v[16:19], v[206:209], v[190:193], v[16:19]
	v_mfma_f32_16x16x32_bf16 v[8:11], v[214:217], v[190:193], v[8:11]
	v_mfma_f32_16x16x32_bf16 v[4:7], v[206:209], v[198:201], v[4:7]
	v_mfma_f32_16x16x32_bf16 v[0:3], v[214:217], v[198:201], v[0:3]
	s_add_u32 s64, s64, 0x100
	s_addc_u32 s65, s65, 0
	s_add_u32 s31, s31, 0x100
	s_addc_u32 s57, s57, 0
	s_cmp_ge_i32 s85, s84
	s_mov_b32 s59, s85
	s_cbranch_scc1 .Leo_exit1
	s_barrier
	s_branch .LBB0_456

;     __device__ __forceinline__ void operator()(const f32x4 (&acc)[2][2][4][2], const Unit& u, int wr, int wc, int fr, int fq) const {
;         const int row0 = u.pm * BM + wr * 64 + fr, col0 = u.pn * BM + wc * 32 + 8 * fq;
;         if (u.part) {
;             float* base = tailacc + (size_t)(u.part - 1) * slab - (size_t)tail_row0 * tail_ld;
; #pragma unroll
;             for (int ai = 0; ai < 2; ++ai)
; #pragma unroll
;                 for (int m = 0; m < 4; ++m) { float* rowp = base + (size_t)(row0 + ai * HALF + m * 16) * tail_ld + col0;
; #pragma unroll
;                     for (int bj = 0; bj < 2; ++bj)
; #pragma unroll
;                         for (int n = 0; n < 2; ++n) *(f32x4*)(rowp + bj * HALF + 4 * n) = acc[ai][bj][m][n]; }
;             return;
.Leo_b1:
	v_lshl_add_u32 v152, s8, 8, v155
	v_lshl_or_b32 v144, s30, 8, v157
	v_or_b32_e32 v150, 16, v152
	v_or_b32_e32 v148, 32, v152
	v_or_b32_e32 v146, 48, v152
	s_cmp_lg_u32 s81, 0
	v_ashrrev_i32_e32 v145, 31, v144
	v_ashrrev_i32_e32 v153, 31, v152
	v_ashrrev_i32_e32 v151, 31, v150
	v_ashrrev_i32_e32 v149, 31, v148
	v_ashrrev_i32_e32 v147, 31, v146
	s_cbranch_scc0 .LBB0_459
	s_add_i32 s8, s81, -1
	s_lshl_b64 s[30:31], s[8:9], 21
	s_add_u32 s30, s4, s30
	s_addc_u32 s31, s5, s31
	v_lshl_add_u64 v[162:163], v[144:145], 2, s[30:31]
	s_brev_b32 s30, 63
	s_mov_b32 s31, -1
	v_lshl_add_u64 v[162:163], v[162:163], 0, s[30:31]
	v_lshlrev_b64 v[164:165], 12, v[152:153]
	v_lshlrev_b64 v[166:167], 12, v[150:151]
	v_lshl_add_u64 v[164:165], v[162:163], 0, v[164:165]
	v_lshl_add_u64 v[166:167], v[162:163], 0, v[166:167]
	global_store_dwordx4 v[164:165], v[124:127], off
	global_store_dwordx4 v[164:165], v[120:123], off offset:16
	global_store_dwordx4 v[164:165], v[112:115], off offset:512
	global_store_dwordx4 v[164:165], v[104:107], off offset:528
	global_store_dwordx4 v[166:167], v[116:119], off
	global_store_dwordx4 v[166:167], v[108:111], off offset:16
	global_store_dwordx4 v[166:167], v[96:99], off offset:512
	global_store_dwordx4 v[166:167], v[88:91], off offset:528
	v_lshlrev_b64 v[166:167], 12, v[148:149]
	v_lshl_add_u64 v[166:167], v[162:163], 0, v[166:167]
	global_store_dwordx4 v[166:167], v[100:103], off
	global_store_dwordx4 v[166:167], v[92:95], off offset:16
	global_store_dwordx4 v[166:167], v[80:83], off offset:512
	global_store_dwordx4 v[166:167], v[72:75], off offset:528
	v_lshlrev_b64 v[166:167], 12, v[146:147]
	s_mov_b32 s8, 0x80000
	v_lshl_add_u64 v[162:163], v[162:163], 0, v[166:167]
	v_add_co_u32_e32 v166, vcc, s8, v164
	s_mov_b64 s[30:31], 0x80000
	s_nop 0
	v_addc_co_u32_e32 v167, vcc, 0, v165, vcc
	s_mov_b32 s8, 0x90000
	global_store_dwordx4 v[162:163], v[84:87], off
	global_store_dwordx4 v[162:163], v[76:79], off offset:16
	global_store_dwordx4 v[162:163], v[68:71], off offset:512
	global_store_dwordx4 v[162:163], v[64:67], off offset:528
	v_lshl_add_u64 v[162:163], v[164:165], 0, s[30:31]
	global_store_dwordx4 v[166:167], v[60:63], off
	global_store_dwordx4 v[162:163], v[56:59], off offset:16
	global_store_dwordx4 v[162:163], v[48:51], off offset:512
	global_store_dwordx4 v[162:163], v[40:43], off offset:528
	v_add_co_u32_e32 v166, vcc, s8, v164
	s_mov_b64 s[30:31], 0x90000
	s_nop 0
	v_addc_co_u32_e32 v167, vcc, 0, v165, vcc
	s_mov_b32 s8, 0xa0000
	v_lshl_add_u64 v[162:163], v[164:165], 0, s[30:31]
	global_store_dwordx4 v[166:167], v[52:55], off
	global_store_dwordx4 v[162:163], v[44:47], off offset:16
	global_store_dwordx4 v[162:163], v[32:35], off offset:512
	global_store_dwordx4 v[162:163], v[24:27], off offset:528
	s_mov_b64 s[30:31], 0xa0000
	v_add_co_u32_e32 v166, vcc, s8, v164
	v_lshl_add_u64 v[162:163], v[164:165], 0, s[30:31]
	s_nop 0
	v_addc_co_u32_e32 v167, vcc, 0, v165, vcc
	s_mov_b64 s[30:31], 0xb0000
	global_store_dwordx4 v[166:167], v[36:39], off
	global_store_dwordx4 v[162:163], v[28:31], off offset:16
	global_store_dwordx4 v[162:163], v[16:19], off offset:512
	global_store_dwordx4 v[162:163], v[8:11], off offset:528
	v_lshl_add_u64 v[162:163], v[164:165], 0, s[30:31]
	v_add_co_u32_e32 v164, vcc, 0xb0000, v164
	s_nop 1
	v_addc_co_u32_e32 v165, vcc, 0, v165, vcc
	global_store_dwordx4 v[164:165], v[20:23], off
	global_store_dwordx4 v[162:163], v[12:15], off offset:16
	global_store_dwordx4 v[162:163], v[4:7], off offset:512
	global_store_dwordx4 v[162:163], v[0:3], off offset:528
	s_cbranch_execnz .LBB0_441
	s_branch .LBB0_440

; template <class Epi>
; __device__ __forceinline__ void gemm_phase(LAS unsigned char* lds, const Gemm g, const StaticOrder& S, const Epi& E) {
;     ...
;     for (;;) {
;         const bool has_next = S.next(ui + 1, nxt);
;         const char* nA = has_next ? (const char*)g.A + (size_t)nxt.pm * tstepA + (size_t)nxt.kt0 * kstep : cA; const char* nB = has_next ? (const char*)g.Bt + (size_t)nxt.pn * tstepB + (size_t)nxt.kt0 * kstep : cB;
;         const int nt = cur.nkt;
.LBB0_674:
	s_or_b64 exec, exec, s[58:59]
	s_cmpk_gt_u32 s3, 0xff
	s_cbranch_scc0 .Leo_l2
	s_barrier
.Leo_l2:
	s_and_b64 vcc, exec, s[6:7]
	s_mov_b32 s59, s36
	s_mov_b32 s58, s38
	s_mov_b64 s[62:63], s[56:57]
	s_mov_b64 s[60:61], s[40:41]
	s_cbranch_vccnz .LBB0_691

; #define PG8_STAGE(bufoff, gbase, voff) do { _Pragma("unroll") for (int _i = 0; _i < 2; ++_i) \
;         __builtin_amdgcn_global_load_lds((const unsigned*)((const char*)(gbase) + (voff)[_i]), (LAS unsigned*)(lds + (bufoff) + ldsw + _i * 8192), 16, 0, 0); } while (0)
; #define PG8_LDA(dst, b, h) do { _Pragma("unroll") for (int m = 0; m < 4; ++m) _Pragma("unroll") for (int k = 0; k < 2; ++k) dst[m][k] = *(const LAS bf16x8*)(lds + PG8_SA(b, h) + aoff + m * 2048 + k * 1024); } while (0)
; #define PG8_LDB(dst, b, h) do { _Pragma("unroll") for (int n = 0; n < 2; ++n) _Pragma("unroll") for (int k = 0; k < 2; ++k) dst[n][k] = *(const LAS bf16x8*)(lds + PG8_SB(b, h) + boff + n * 2048 + k * 1024); } while (0)
; #define PG8_MMA(ai, bj, At, Bt) do { __builtin_amdgcn_s_setprio(1); _Pragma("unroll") for (int m = 0; m < 4; ++m) _Pragma("unroll") for (int n = 0; n < 2; ++n) _Pragma("unroll") for (int k = 0; k < 2; ++k) \
;         acc[ai][bj][m][n] = __builtin_amdgcn_mfma_f32_16x16x32_bf16(Bt[n][k], At[m][k], acc[ai][bj][m][n], 0, 0, 0); __builtin_amdgcn_s_setprio(0); } while (0)
; #define PG8_WAIT_V(n) asm volatile("s_waitcnt vmcnt(" #n ")" ::: "memory")
; #define PG8_WAIT_L(n) asm volatile("s_waitcnt lgkmcnt(" #n ")" ::: "memory")
; template <class Epi>
; __device__ __forceinline__ void gemm_phase(LAS unsigned char* lds, const Gemm g, const StaticOrder& S, const Epi& E) {
;     ...
;         for (int t = 0; t < nt; t += 2) {
;             const bool last = (t == nt - 2);
;             const char* a1 = cA + (size_t)(t + 1) * kstep;
;             const char* a2 = last ? nA : cA + (size_t)(t + 2) * kstep; const char* b2 = last ? nB : cB + (size_t)(t + 2) * kstep;
;             const char* a3 = a2 + kstep; const char* b3 = b2 + kstep;
;             PG8_LDB(B0, 0, 0); PG8_SCHED; PG8_LDA(At, 0, 0); PG8_STAGE(PG8_SA(1, 1), a1 + hstepA, voffA);
;             PG8_WAIT_L(8); PG8_BAR; PG8_WAIT_L(0); PG8_MMA(0, 0, At, B0); PG8_BAR; PG8_SCHED;
;             PG8_LDB(B1, 0, 1); PG8_STAGE(PG8_SB(0, 0), b2, voffB);
;             PG8_BAR; PG8_WAIT_L(0); PG8_MMA(0, 1, At, B1); PG8_BAR;
;             PG8_LDA(At, 0, 1); PG8_STAGE(PG8_SA(0, 0), a2, voffA);
;             PG8_BAR; PG8_WAIT_L(0); PG8_MMA(1, 0, At, B0); PG8_BAR; PG8_SCHED;
;             PG8_STAGE(PG8_SB(0, 1), b2 + hstepB, voffB);
;             PG8_WAIT_V(6); PG8_BAR; PG8_MMA(1, 1, At, B1); PG8_BAR;
.LBB0_682:
	s_add_u32 s62, s60, 0xfffc0080
	s_addc_u32 s63, s61, -1
	s_cmp_eq_u32 s78, 12
	s_cselect_b32 s65, s41, s63
	s_cselect_b32 s64, s40, s62
	s_cselect_b32 s63, s57, s39
	s_cselect_b32 s62, s56, s37
	ds_read_b128 v[152:155], v159
	ds_read_b128 v[162:165], v159 offset:1024
	ds_read_b128 v[166:169], v159 offset:2048
	ds_read_b128 v[170:173], v159 offset:3072
	ds_read_b128 v[174:177], v160
	ds_read_b128 v[178:181], v160 offset:1024
	ds_read_b128 v[182:185], v160 offset:2048
	ds_read_b128 v[186:189], v160 offset:3072
	ds_read_b128 v[190:193], v160 offset:4096
	ds_read_b128 v[194:197], v160 offset:5120
	ds_read_b128 v[198:201], v160 offset:6144
	ds_read_b128 v[202:205], v160 offset:7168
	ds_read_b128 v[206:209], v161
	ds_read_b128 v[210:213], v161 offset:1024
	ds_read_b128 v[214:217], v161 offset:2048
	ds_read_b128 v[218:221], v161 offset:3072
	s_add_i32 m0, s35, 0xc000
	v_lshl_add_u64 v[242:243], s[60:61], 0, v[144:145]
	global_load_lds_dwordx4 v[242:243], off
	s_add_i32 m0, s35, 0xe000
	v_lshl_add_u64 v[242:243], s[60:61], 0, v[146:147]
	global_load_lds_dwordx4 v[242:243], off
	s_waitcnt vmcnt(8) lgkmcnt(0)
	s_barrier
	v_mfma_f32_16x16x32_bf16 v[124:127], v[152:155], v[174:177], v[124:127]
	v_mfma_f32_16x16x32_bf16 v[120:123], v[166:169], v[174:177], v[120:123]
	v_mfma_f32_16x16x32_bf16 v[116:119], v[152:155], v[182:185], v[116:119]
	v_mfma_f32_16x16x32_bf16 v[108:111], v[166:169], v[182:185], v[108:111]
	v_mfma_f32_16x16x32_bf16 v[100:103], v[152:155], v[190:193], v[100:103]
	v_mfma_f32_16x16x32_bf16 v[92:95], v[166:169], v[190:193], v[92:95]
	v_mfma_f32_16x16x32_bf16 v[84:87], v[152:155], v[198:201], v[84:87]
	v_mfma_f32_16x16x32_bf16 v[76:79], v[166:169], v[198:201], v[76:79]
	v_mfma_f32_16x16x32_bf16 v[124:127], v[162:165], v[178:181], v[124:127]
	v_mfma_f32_16x16x32_bf16 v[120:123], v[170:173], v[178:181], v[120:123]
	v_mfma_f32_16x16x32_bf16 v[116:119], v[162:165], v[186:189], v[116:119]
	v_mfma_f32_16x16x32_bf16 v[108:111], v[170:173], v[186:189], v[108:111]
	v_mfma_f32_16x16x32_bf16 v[100:103], v[162:165], v[194:197], v[100:103]
	v_mfma_f32_16x16x32_bf16 v[92:95], v[170:173], v[194:197], v[92:95]
	v_mfma_f32_16x16x32_bf16 v[84:87], v[162:165], v[202:205], v[84:87]
	v_mfma_f32_16x16x32_bf16 v[76:79], v[170:173], v[202:205], v[76:79]
	v_mfma_f32_16x16x32_bf16 v[112:115], v[206:209], v[174:177], v[112:115]
	v_mfma_f32_16x16x32_bf16 v[104:107], v[214:217], v[174:177], v[104:107]
	v_mfma_f32_16x16x32_bf16 v[96:99], v[206:209], v[182:185], v[96:99]
	v_mfma_f32_16x16x32_bf16 v[88:91], v[214:217], v[182:185], v[88:91]
	v_mfma_f32_16x16x32_bf16 v[80:83], v[206:209], v[190:193], v[80:83]
	v_mfma_f32_16x16x32_bf16 v[72:75], v[214:217], v[190:193], v[72:75]
	v_mfma_f32_16x16x32_bf16 v[68:71], v[206:209], v[198:201], v[68:71]
	v_mfma_f32_16x16x32_bf16 v[64:67], v[214:217], v[198:201], v[64:67]
	v_mfma_f32_16x16x32_bf16 v[112:115], v[210:213], v[178:181], v[112:115]
	v_mfma_f32_16x16x32_bf16 v[104:107], v[218:221], v[178:181], v[104:107]
	v_mfma_f32_16x16x32_bf16 v[96:99], v[210:213], v[186:189], v[96:99]
	v_mfma_f32_16x16x32_bf16 v[88:91], v[218:221], v[186:189], v[88:91]
	v_mfma_f32_16x16x32_bf16 v[80:83], v[210:213], v[194:197], v[80:83]
	v_mfma_f32_16x16x32_bf16 v[72:75], v[218:221], v[194:197], v[72:75]
	v_mfma_f32_16x16x32_bf16 v[68:71], v[210:213], v[202:205], v[68:71]
	v_mfma_f32_16x16x32_bf16 v[64:67], v[218:221], v[202:205], v[64:67]
	s_barrier
	ds_read_b128 v[174:177], v160 offset:16384
	ds_read_b128 v[178:181], v160 offset:17408
	ds_read_b128 v[182:185], v160 offset:18432
	ds_read_b128 v[186:189], v160 offset:19456
	ds_read_b128 v[190:193], v160 offset:20480
	ds_read_b128 v[194:197], v160 offset:21504
	ds_read_b128 v[198:201], v160 offset:22528
	ds_read_b128 v[202:205], v160 offset:23552
	s_add_i32 s79, s75, s33
	s_mov_b32 m0, s79
	v_lshl_add_u64 v[222:223], s[62:63], 0, v[138:139]
	global_load_lds_dwordx4 v[222:223], off
	s_add_i32 m0, s79, 0x2000
	v_lshl_add_u64 v[224:225], s[62:63], 0, v[142:143]
	global_load_lds_dwordx4 v[224:225], off
	s_mov_b32 m0, s35
	v_lshl_add_u64 v[226:227], s[64:65], 0, v[136:137]
	global_load_lds_dwordx4 v[226:227], off
	s_mov_b32 m0, s66
	v_lshl_add_u64 v[228:229], s[64:65], 0, v[140:141]
	global_load_lds_dwordx4 v[228:229], off
	s_add_u32 s80, s62, 0x40000
	s_addc_u32 s81, s63, 0
	s_add_i32 s79, s76, s33
	s_mov_b32 m0, s79
	v_lshl_add_u64 v[240:241], s[80:81], 0, v[138:139]
	global_load_lds_dwordx4 v[240:241], off
	s_add_i32 m0, s79, 0x2000
	v_lshl_add_u64 v[240:241], s[80:81], 0, v[142:143]
	global_load_lds_dwordx4 v[240:241], off
	s_waitcnt vmcnt(8) lgkmcnt(0)
	s_barrier
; #define PG8_STAGE(bufoff, gbase, voff) do { _Pragma("unroll") for (int _i = 0; _i < 2; ++_i) \
;         __builtin_amdgcn_global_load_lds((const unsigned*)((const char*)(gbase) + (voff)[_i]), (LAS unsigned*)(lds + (bufoff) + ldsw + _i * 8192), 16, 0, 0); } while (0)
; #define PG8_LDA(dst, b, h) do { _Pragma("unroll") for (int m = 0; m < 4; ++m) _Pragma("unroll") for (int k = 0; k < 2; ++k) dst[m][k] = *(const LAS bf16x8*)(lds + PG8_SA(b, h) + aoff + m * 2048 + k * 1024); } while (0)
; #define PG8_LDB(dst, b, h) do { _Pragma("unroll") for (int n = 0; n < 2; ++n) _Pragma("unroll") for (int k = 0; k < 2; ++k) dst[n][k] = *(const LAS bf16x8*)(lds + PG8_SB(b, h) + boff + n * 2048 + k * 1024); } while (0)
; #define PG8_MMA(ai, bj, At, Bt) do { __builtin_amdgcn_s_setprio(1); _Pragma("unroll") for (int m = 0; m < 4; ++m) _Pragma("unroll") for (int n = 0; n < 2; ++n) _Pragma("unroll") for (int k = 0; k < 2; ++k) \
;         acc[ai][bj][m][n] = __builtin_amdgcn_mfma_f32_16x16x32_bf16(Bt[n][k], At[m][k], acc[ai][bj][m][n], 0, 0, 0); __builtin_amdgcn_s_setprio(0); } while (0)
; #define PG8_WAIT_V(n) asm volatile("s_waitcnt vmcnt(" #n ")" ::: "memory")
; #define PG8_WAIT_L(n) asm volatile("s_waitcnt lgkmcnt(" #n ")" ::: "memory")
; #define PG8_BAR __builtin_amdgcn_s_barrier()
; #define PG8_SCHED __builtin_amdgcn_sched_barrier(0)
; template <class Epi>
; __device__ __forceinline__ void gemm_phase(LAS unsigned char* lds, const Gemm g, const StaticOrder& S, const Epi& E) {
;     ...
;             PG8_WAIT_V(6); PG8_BAR; PG8_MMA(1, 1, At, B1); PG8_BAR;
;             PG8_LDB(B0, 1, 0); PG8_SCHED; PG8_LDA(At, 1, 0); PG8_STAGE(PG8_SA(0, 1), a2 + hstepA, voffA);
;             PG8_WAIT_L(8); PG8_BAR; PG8_WAIT_L(0); PG8_MMA(0, 0, At, B0); PG8_BAR; PG8_SCHED;
;             PG8_LDB(B1, 1, 1); PG8_STAGE(PG8_SB(1, 0), b3, voffB);
;             PG8_BAR; PG8_WAIT_L(0); PG8_MMA(0, 1, At, B1); PG8_BAR;
;             PG8_LDA(At, 1, 1); PG8_STAGE(PG8_SA(1, 0), a3, voffA);
;             PG8_BAR; PG8_WAIT_L(0); PG8_MMA(1, 0, At, B0); PG8_BAR; PG8_SCHED;
	v_mfma_f32_16x16x32_bf16 v[60:63], v[152:155], v[174:177], v[60:63]
	v_mfma_f32_16x16x32_bf16 v[56:59], v[166:169], v[174:177], v[56:59]
	v_mfma_f32_16x16x32_bf16 v[52:55], v[152:155], v[182:185], v[52:55]
	v_mfma_f32_16x16x32_bf16 v[44:47], v[166:169], v[182:185], v[44:47]
	v_mfma_f32_16x16x32_bf16 v[36:39], v[152:155], v[190:193], v[36:39]
	v_mfma_f32_16x16x32_bf16 v[28:31], v[166:169], v[190:193], v[28:31]
	v_mfma_f32_16x16x32_bf16 v[20:23], v[152:155], v[198:201], v[20:23]
	v_mfma_f32_16x16x32_bf16 v[12:15], v[166:169], v[198:201], v[12:15]
	v_mfma_f32_16x16x32_bf16 v[60:63], v[162:165], v[178:181], v[60:63]
	v_mfma_f32_16x16x32_bf16 v[56:59], v[170:173], v[178:181], v[56:59]
	v_mfma_f32_16x16x32_bf16 v[52:55], v[162:165], v[186:189], v[52:55]
	v_mfma_f32_16x16x32_bf16 v[44:47], v[170:173], v[186:189], v[44:47]
	v_mfma_f32_16x16x32_bf16 v[36:39], v[162:165], v[194:197], v[36:39]
	v_mfma_f32_16x16x32_bf16 v[28:31], v[170:173], v[194:197], v[28:31]
	v_mfma_f32_16x16x32_bf16 v[20:23], v[162:165], v[202:205], v[20:23]
	v_mfma_f32_16x16x32_bf16 v[12:15], v[170:173], v[202:205], v[12:15]
	v_mfma_f32_16x16x32_bf16 v[48:51], v[206:209], v[174:177], v[48:51]
	v_mfma_f32_16x16x32_bf16 v[40:43], v[214:217], v[174:177], v[40:43]
	v_mfma_f32_16x16x32_bf16 v[32:35], v[206:209], v[182:185], v[32:35]
	v_mfma_f32_16x16x32_bf16 v[24:27], v[214:217], v[182:185], v[24:27]
	v_mfma_f32_16x16x32_bf16 v[16:19], v[206:209], v[190:193], v[16:19]
	v_mfma_f32_16x16x32_bf16 v[8:11], v[214:217], v[190:193], v[8:11]
	v_mfma_f32_16x16x32_bf16 v[4:7], v[206:209], v[198:201], v[4:7]
	v_mfma_f32_16x16x32_bf16 v[0:3], v[214:217], v[198:201], v[0:3]
	v_mfma_f32_16x16x32_bf16 v[48:51], v[210:213], v[178:181], v[48:51]
	v_mfma_f32_16x16x32_bf16 v[40:43], v[218:221], v[178:181], v[40:43]
	v_mfma_f32_16x16x32_bf16 v[32:35], v[210:213], v[186:189], v[32:35]
	v_mfma_f32_16x16x32_bf16 v[24:27], v[218:221], v[186:189], v[24:27]
	v_mfma_f32_16x16x32_bf16 v[16:19], v[210:213], v[194:197], v[16:19]
	v_mfma_f32_16x16x32_bf16 v[8:11], v[218:221], v[194:197], v[8:11]
	v_mfma_f32_16x16x32_bf16 v[4:7], v[210:213], v[202:205], v[4:7]
	v_mfma_f32_16x16x32_bf16 v[0:3], v[218:221], v[202:205], v[0:3]
	s_barrier
	s_add_i32 s79, 0, 0x18000
	v_add_u32_e32 v170, s79, v156
	ds_read_b128 v[152:155], v170
	ds_read_b128 v[162:165], v170 offset:1024
	ds_read_b128 v[166:169], v170 offset:2048
	ds_read_b128 v[170:173], v170 offset:3072
	ds_read_b128 v[174:177], v160 offset:32768
	ds_read_b128 v[178:181], v160 offset:33792
	ds_read_b128 v[182:185], v160 offset:34816
	ds_read_b128 v[186:189], v160 offset:35840
	ds_read_b128 v[190:193], v160 offset:36864
	ds_read_b128 v[194:197], v160 offset:37888
	ds_read_b128 v[198:201], v160 offset:38912
	ds_read_b128 v[202:205], v160 offset:39936
	s_add_i32 s98, 0, 0x1c000
	v_add_u32_e32 v218, s98, v156
	ds_read_b128 v[206:209], v218
	ds_read_b128 v[210:213], v218 offset:1024
	ds_read_b128 v[214:217], v218 offset:2048
	ds_read_b128 v[218:221], v218 offset:3072
	s_add_u32 s64, s64, 0x40000
	s_addc_u32 s65, s65, 0
	s_mov_b32 m0, s67
	v_lshl_add_u64 v[244:245], s[64:65], 0, v[136:137]
	global_load_lds_dwordx4 v[244:245], off
	s_mov_b32 m0, s68
	v_lshl_add_u64 v[244:245], s[64:65], 0, v[140:141]
	global_load_lds_dwordx4 v[244:245], off
	s_waitcnt vmcnt(8) lgkmcnt(0)
	s_barrier
	v_mfma_f32_16x16x32_bf16 v[124:127], v[152:155], v[174:177], v[124:127]
	v_mfma_f32_16x16x32_bf16 v[120:123], v[166:169], v[174:177], v[120:123]
	v_mfma_f32_16x16x32_bf16 v[116:119], v[152:155], v[182:185], v[116:119]
	v_mfma_f32_16x16x32_bf16 v[108:111], v[166:169], v[182:185], v[108:111]
	v_mfma_f32_16x16x32_bf16 v[100:103], v[152:155], v[190:193], v[100:103]
	v_mfma_f32_16x16x32_bf16 v[92:95], v[166:169], v[190:193], v[92:95]
	v_mfma_f32_16x16x32_bf16 v[84:87], v[152:155], v[198:201], v[84:87]
	v_mfma_f32_16x16x32_bf16 v[76:79], v[166:169], v[198:201], v[76:79]
	v_mfma_f32_16x16x32_bf16 v[124:127], v[162:165], v[178:181], v[124:127]
	v_mfma_f32_16x16x32_bf16 v[120:123], v[170:173], v[178:181], v[120:123]
	v_mfma_f32_16x16x32_bf16 v[116:119], v[162:165], v[186:189], v[116:119]
	v_mfma_f32_16x16x32_bf16 v[108:111], v[170:173], v[186:189], v[108:111]
	v_mfma_f32_16x16x32_bf16 v[100:103], v[162:165], v[194:197], v[100:103]
	v_mfma_f32_16x16x32_bf16 v[92:95], v[170:173], v[194:197], v[92:95]
	v_mfma_f32_16x16x32_bf16 v[84:87], v[162:165], v[202:205], v[84:87]
	v_mfma_f32_16x16x32_bf16 v[76:79], v[170:173], v[202:205], v[76:79]
	v_mfma_f32_16x16x32_bf16 v[112:115], v[206:209], v[174:177], v[112:115]
	v_mfma_f32_16x16x32_bf16 v[104:107], v[214:217], v[174:177], v[104:107]
	v_mfma_f32_16x16x32_bf16 v[96:99], v[206:209], v[182:185], v[96:99]
	v_mfma_f32_16x16x32_bf16 v[88:91], v[214:217], v[182:185], v[88:91]
	v_mfma_f32_16x16x32_bf16 v[80:83], v[206:209], v[190:193], v[80:83]
	v_mfma_f32_16x16x32_bf16 v[72:75], v[214:217], v[190:193], v[72:75]
	v_mfma_f32_16x16x32_bf16 v[68:71], v[206:209], v[198:201], v[68:71]
	v_mfma_f32_16x16x32_bf16 v[64:67], v[214:217], v[198:201], v[64:67]
	v_mfma_f32_16x16x32_bf16 v[112:115], v[210:213], v[178:181], v[112:115]
	v_mfma_f32_16x16x32_bf16 v[104:107], v[218:221], v[178:181], v[104:107]
	v_mfma_f32_16x16x32_bf16 v[96:99], v[210:213], v[186:189], v[96:99]
	v_mfma_f32_16x16x32_bf16 v[88:91], v[218:221], v[186:189], v[88:91]
	v_mfma_f32_16x16x32_bf16 v[80:83], v[210:213], v[194:197], v[80:83]
	v_mfma_f32_16x16x32_bf16 v[72:75], v[218:221], v[194:197], v[72:75]
	v_mfma_f32_16x16x32_bf16 v[68:71], v[210:213], v[202:205], v[68:71]
	v_mfma_f32_16x16x32_bf16 v[64:67], v[218:221], v[202:205], v[64:67]
	s_barrier
; #define PG8_STAGE(bufoff, gbase, voff) do { _Pragma("unroll") for (int _i = 0; _i < 2; ++_i) \
;         __builtin_amdgcn_global_load_lds((const unsigned*)((const char*)(gbase) + (voff)[_i]), (LAS unsigned*)(lds + (bufoff) + ldsw + _i * 8192), 16, 0, 0); } while (0)
; #define PG8_LDA(dst, b, h) do { _Pragma("unroll") for (int m = 0; m < 4; ++m) _Pragma("unroll") for (int k = 0; k < 2; ++k) dst[m][k] = *(const LAS bf16x8*)(lds + PG8_SA(b, h) + aoff + m * 2048 + k * 1024); } while (0)
; #define PG8_MMA(ai, bj, At, Bt) do { __builtin_amdgcn_s_setprio(1); _Pragma("unroll") for (int m = 0; m < 4; ++m) _Pragma("unroll") for (int n = 0; n < 2; ++n) _Pragma("unroll") for (int k = 0; k < 2; ++k) \
;         acc[ai][bj][m][n] = __builtin_amdgcn_mfma_f32_16x16x32_bf16(Bt[n][k], At[m][k], acc[ai][bj][m][n], 0, 0, 0); __builtin_amdgcn_s_setprio(0); } while (0)
; #define PG8_WAIT_V(n) asm volatile("s_waitcnt vmcnt(" #n ")" ::: "memory")
; #define PG8_WAIT_L(n) asm volatile("s_waitcnt lgkmcnt(" #n ")" ::: "memory")
; #define PG8_BAR __builtin_amdgcn_s_barrier()
; #define PG8_SCHED __builtin_amdgcn_sched_barrier(0)
; template <class Epi>
; __device__ __forceinline__ void gemm_phase(LAS unsigned char* lds, const Gemm g, const StaticOrder& S, const Epi& E) {
;     ...
;             PG8_LDA(At, 1, 1); PG8_STAGE(PG8_SA(1, 0), a3, voffA);
;             PG8_BAR; PG8_WAIT_L(0); PG8_MMA(1, 0, At, B0); PG8_BAR; PG8_SCHED;
;             PG8_STAGE(PG8_SB(1, 1), b3 + hstepB, voffB);
;             PG8_WAIT_V(6); PG8_BAR; PG8_MMA(1, 1, At, B1); PG8_BAR;
;         }
	ds_read_b128 v[174:177], v160 offset:49152
	ds_read_b128 v[178:181], v160 offset:50176
	ds_read_b128 v[182:185], v160 offset:51200
	ds_read_b128 v[186:189], v160 offset:52224
	ds_read_b128 v[190:193], v160 offset:53248
	ds_read_b128 v[194:197], v160 offset:54272
	ds_read_b128 v[198:201], v160 offset:55296
	ds_read_b128 v[202:205], v160 offset:56320
	s_add_i32 s65, s79, s33
	s_mov_b32 m0, s65
	v_lshl_add_u64 v[222:223], v[222:223], 0, s[28:29]
	global_load_lds_dwordx4 v[222:223], off
	s_add_i32 m0, s65, 0x2000
	v_lshl_add_u64 v[222:223], v[224:225], 0, s[28:29]
	global_load_lds_dwordx4 v[222:223], off
	s_mov_b32 m0, s71
	v_lshl_add_u64 v[222:223], v[226:227], 0, s[28:29]
	global_load_lds_dwordx4 v[222:223], off
	s_mov_b32 m0, s72
	v_lshl_add_u64 v[222:223], v[228:229], 0, s[28:29]
	global_load_lds_dwordx4 v[222:223], off
	s_add_u32 s62, s62, 0x40080
	s_addc_u32 s63, s63, 0
	s_add_i32 s64, s98, s33
	s_mov_b32 m0, s64
	v_lshl_add_u64 v[240:241], s[62:63], 0, v[138:139]
	global_load_lds_dwordx4 v[240:241], off
	s_add_i32 m0, s64, 0x2000
	v_lshl_add_u64 v[240:241], s[62:63], 0, v[142:143]
	global_load_lds_dwordx4 v[240:241], off
	s_waitcnt vmcnt(8) lgkmcnt(0)
	s_barrier
	v_mfma_f32_16x16x32_bf16 v[60:63], v[152:155], v[174:177], v[60:63]
	v_mfma_f32_16x16x32_bf16 v[56:59], v[166:169], v[174:177], v[56:59]
	v_mfma_f32_16x16x32_bf16 v[52:55], v[152:155], v[182:185], v[52:55]
	v_mfma_f32_16x16x32_bf16 v[44:47], v[166:169], v[182:185], v[44:47]
	v_mfma_f32_16x16x32_bf16 v[36:39], v[152:155], v[190:193], v[36:39]
	v_mfma_f32_16x16x32_bf16 v[28:31], v[166:169], v[190:193], v[28:31]
	v_mfma_f32_16x16x32_bf16 v[20:23], v[152:155], v[198:201], v[20:23]
	v_mfma_f32_16x16x32_bf16 v[12:15], v[166:169], v[198:201], v[12:15]
	v_mfma_f32_16x16x32_bf16 v[60:63], v[162:165], v[178:181], v[60:63]
	v_mfma_f32_16x16x32_bf16 v[56:59], v[170:173], v[178:181], v[56:59]
	v_mfma_f32_16x16x32_bf16 v[52:55], v[162:165], v[186:189], v[52:55]
	v_mfma_f32_16x16x32_bf16 v[44:47], v[170:173], v[186:189], v[44:47]
	v_mfma_f32_16x16x32_bf16 v[36:39], v[162:165], v[194:197], v[36:39]
	v_mfma_f32_16x16x32_bf16 v[28:31], v[170:173], v[194:197], v[28:31]
	v_mfma_f32_16x16x32_bf16 v[20:23], v[162:165], v[202:205], v[20:23]
	v_mfma_f32_16x16x32_bf16 v[12:15], v[170:173], v[202:205], v[12:15]
	v_mfma_f32_16x16x32_bf16 v[48:51], v[206:209], v[174:177], v[48:51]
	v_mfma_f32_16x16x32_bf16 v[40:43], v[214:217], v[174:177], v[40:43]
	v_mfma_f32_16x16x32_bf16 v[32:35], v[206:209], v[182:185], v[32:35]
	v_mfma_f32_16x16x32_bf16 v[24:27], v[214:217], v[182:185], v[24:27]
	v_mfma_f32_16x16x32_bf16 v[16:19], v[206:209], v[190:193], v[16:19]
	v_mfma_f32_16x16x32_bf16 v[8:11], v[214:217], v[190:193], v[8:11]
	v_mfma_f32_16x16x32_bf16 v[4:7], v[206:209], v[198:201], v[4:7]
	v_mfma_f32_16x16x32_bf16 v[0:3], v[214:217], v[198:201], v[0:3]
	v_mfma_f32_16x16x32_bf16 v[48:51], v[210:213], v[178:181], v[48:51]
	v_mfma_f32_16x16x32_bf16 v[40:43], v[218:221], v[178:181], v[40:43]
	v_mfma_f32_16x16x32_bf16 v[32:35], v[210:213], v[186:189], v[32:35]
	v_mfma_f32_16x16x32_bf16 v[24:27], v[218:221], v[186:189], v[24:27]
	v_mfma_f32_16x16x32_bf16 v[16:19], v[210:213], v[194:197], v[16:19]
	v_mfma_f32_16x16x32_bf16 v[8:11], v[218:221], v[194:197], v[8:11]
	v_mfma_f32_16x16x32_bf16 v[4:7], v[210:213], v[202:205], v[4:7]
	v_mfma_f32_16x16x32_bf16 v[0:3], v[218:221], v[202:205], v[0:3]
	s_add_i32 s78, s78, 2
	s_add_u32 s60, s60, 0x100
	s_addc_u32 s61, s61, 0
	s_add_u32 s37, s37, 0x100
	s_addc_u32 s39, s39, 0
	s_cmp_gt_u32 s78, 13
	s_cbranch_scc1 .Leo_exit2
	s_barrier
	s_branch .LBB0_682

; __device__ __forceinline__ unsigned pk2(float lo, float hi) { unsigned r; asm("v_cvt_pk_bf16_f32 %0, %1, %2" : "=v"(r) : "v"(lo), "v"(hi)); return r; }
; __device__ __forceinline__ float gelu_t(float x) { return x * __builtin_amdgcn_rcpf(1.f + __expf(-1.5957691216057308f * (x + 0.044715f * x * x * x))); }
;     __device__ __forceinline__ void operator()(const f32x4 (&acc)[2][2][4][2], const Unit& u, int wr, int wc, int fr, int fq) const {
;     ...
; #pragma unroll
;         for (int ai = 0; ai < 2; ++ai)
; #pragma unroll
;             for (int m = 0; m < 4; ++m) { const int row = row0 + ai * HALF + m * 16; u16* rowp = O + (size_t)row * ldc + col0;
; #pragma unroll
;                 for (int bj = 0; bj < 2; ++bj) { f32x4 v0 = acc[ai][bj][m][0], v1 = acc[ai][bj][m][1];
;                     if (col0 + bj * HALF >= gelu_from) { v0 = (f32x4){gelu_t(v0.x), gelu_t(v0.y), gelu_t(v0.z), gelu_t(v0.w)}; v1 = (f32x4){gelu_t(v1.x), gelu_t(v1.y), gelu_t(v1.z), gelu_t(v1.w)}; }
;                     u32x4 w; w.x = pk2(v0[0], v0[1]); w.y = pk2(v0[2], v0[3]); w.z = pk2(v1[0], v1[1]); w.w = pk2(v1[2], v1[3]);
;                     *(u32x4*)(rowp + bj * HALF) = w;
;                     if (halo != nullptr && m == 3 && fr >= 14) *(u32x4*)(halo + (size_t)((row >> 6) * 2 + (fr - 14)) * ldc + col0 + bj * HALF) = w; } }
.Leo_b2:
	s_lshl_b32 s37, s58, 8
	s_add_i32 s37, s37, s70
	v_lshl_or_b32 v152, s59, 8, v158
	v_or_b32_e32 v162, s37, v135
	v_ashrrev_i32_e32 v153, 31, v152
	v_mov_b64_e32 v[164:165], s[4:5]
	v_mad_i64_i32 v[166:167], s[58:59], v162, s77, v[164:165]
	v_lshlrev_b64 v[154:155], 1, v[152:153]
	v_cvt_pk_bf16_f32 v112, v112, v113
	v_cvt_pk_bf16_f32 v113, v114, v115
	v_cvt_pk_bf16_f32 v114, v104, v105
	v_or_b32_e32 v104, 16, v162
	v_lshl_add_u64 v[166:167], v[166:167], 0, v[154:155]
	v_mad_i64_i32 v[104:105], s[58:59], v104, s77, v[164:165]
	v_cvt_pk_bf16_f32 v96, v96, v97
	v_cvt_pk_bf16_f32 v97, v98, v99
	v_cvt_pk_bf16_f32 v98, v88, v89
	v_or_b32_e32 v88, 32, v162
	v_cvt_pk_bf16_f32 v115, v106, v107
	global_store_dwordx4 v[166:167], v[112:115], off offset:256
	v_mad_i64_i32 v[88:89], s[58:59], v88, s77, v[164:165]
	s_nop 0
	v_lshl_add_u64 v[112:113], v[104:105], 0, v[154:155]
	v_cvt_pk_bf16_f32 v80, v80, v81
	v_cvt_pk_bf16_f32 v81, v82, v83
	v_cvt_pk_bf16_f32 v82, v72, v73
	v_or_b32_e32 v72, 48, v162
	s_ashr_i32 s37, s37, 5
	v_cvt_pk_bf16_f32 v99, v90, v91
	global_store_dwordx4 v[112:113], v[96:99], off offset:256
	v_mad_i64_i32 v[72:73], s[58:59], v72, s77, v[164:165]
	s_nop 0
	v_lshl_add_u64 v[96:97], v[88:89], 0, v[154:155]
	v_add_u32_e32 v163, s37, v157
	v_cvt_pk_bf16_f32 v83, v74, v75
	global_store_dwordx4 v[96:97], v[80:83], off offset:256
	v_cvt_pk_bf16_f32 v124, v124, v125
	v_cvt_pk_bf16_f32 v125, v126, v127
	v_cvt_pk_bf16_f32 v126, v120, v121
	v_cvt_pk_bf16_f32 v127, v122, v123
	global_store_dwordx4 v[166:167], v[124:127], off
	s_nop 0
	v_lshl_add_u64 v[80:81], v[72:73], 0, v[154:155]
	v_cvt_pk_bf16_f32 v104, v116, v117
	v_cvt_pk_bf16_f32 v105, v118, v119
	v_cvt_pk_bf16_f32 v106, v108, v109
	v_cvt_pk_bf16_f32 v107, v110, v111
	global_store_dwordx4 v[112:113], v[104:107], off
	v_cvt_pk_bf16_f32 v88, v100, v101
	v_cvt_pk_bf16_f32 v89, v102, v103
	v_cvt_pk_bf16_f32 v90, v92, v93
	v_cvt_pk_bf16_f32 v91, v94, v95
	global_store_dwordx4 v[96:97], v[88:91], off
	v_cvt_pk_bf16_f32 v72, v84, v85
	v_cvt_pk_bf16_f32 v73, v86, v87
	v_cvt_pk_bf16_f32 v74, v76, v77
	v_cvt_pk_bf16_f32 v75, v78, v79
	global_store_dwordx4 v[80:81], v[72:75], off
	s_and_saveexec_b64 s[58:59], s[0:1]
	s_cbranch_execz .LBB0_685
	v_mov_b64_e32 v[76:77], s[18:19]
	v_mad_i64_i32 v[76:77], s[60:61], v163, s77, v[76:77]
	v_lshl_add_u64 v[76:77], v[152:153], 1, v[76:77]
	global_store_dwordx4 v[76:77], v[72:75], off

; #define PG8_STAGE(bufoff, gbase, voff) do { _Pragma("unroll") for (int _i = 0; _i < 2; ++_i) \
;         __builtin_amdgcn_global_load_lds((const unsigned*)((const char*)(gbase) + (voff)[_i]), (LAS unsigned*)(lds + (bufoff) + ldsw + _i * 8192), 16, 0, 0); } while (0)
; #define PG8_LDA(dst, b, h) do { _Pragma("unroll") for (int m = 0; m < 4; ++m) _Pragma("unroll") for (int k = 0; k < 2; ++k) dst[m][k] = *(const LAS bf16x8*)(lds + PG8_SA(b, h) + aoff + m * 2048 + k * 1024); } while (0)
; #define PG8_LDB(dst, b, h) do { _Pragma("unroll") for (int n = 0; n < 2; ++n) _Pragma("unroll") for (int k = 0; k < 2; ++k) dst[n][k] = *(const LAS bf16x8*)(lds + PG8_SB(b, h) + boff + n * 2048 + k * 1024); } while (0)
; #define PG8_MMA(ai, bj, At, Bt) do { __builtin_amdgcn_s_setprio(1); _Pragma("unroll") for (int m = 0; m < 4; ++m) _Pragma("unroll") for (int n = 0; n < 2; ++n) _Pragma("unroll") for (int k = 0; k < 2; ++k) \
;         acc[ai][bj][m][n] = __builtin_amdgcn_mfma_f32_16x16x32_bf16(Bt[n][k], At[m][k], acc[ai][bj][m][n], 0, 0, 0); __builtin_amdgcn_s_setprio(0); } while (0)
; #define PG8_WAIT_V(n) asm volatile("s_waitcnt vmcnt(" #n ")" ::: "memory")
; #define PG8_WAIT_L(n) asm volatile("s_waitcnt lgkmcnt(" #n ")" ::: "memory")
; template <class Epi>
; __device__ __forceinline__ void gemm_phase(LAS unsigned char* lds, const Gemm g, const StaticOrder& S, const Epi& E) {
;     ...
;         for (int t = 0; t < nt; t += 2) {
;             const bool last = (t == nt - 2);
;             const char* a1 = cA + (size_t)(t + 1) * kstep;
;             const char* a2 = last ? nA : cA + (size_t)(t + 2) * kstep; const char* b2 = last ? nB : cB + (size_t)(t + 2) * kstep;
;             const char* a3 = a2 + kstep; const char* b3 = b2 + kstep;
;             PG8_LDB(B0, 0, 0); PG8_SCHED; PG8_LDA(At, 0, 0); PG8_STAGE(PG8_SA(1, 1), a1 + hstepA, voffA);
;             PG8_WAIT_L(8); PG8_BAR; PG8_WAIT_L(0); PG8_MMA(0, 0, At, B0); PG8_BAR; PG8_SCHED;
;             PG8_LDB(B1, 0, 1); PG8_STAGE(PG8_SB(0, 0), b2, voffB);
;             PG8_BAR; PG8_WAIT_L(0); PG8_MMA(0, 1, At, B1); PG8_BAR;
;             PG8_LDA(At, 0, 1); PG8_STAGE(PG8_SA(0, 0), a2, voffA);
;             PG8_BAR; PG8_WAIT_L(0); PG8_MMA(1, 0, At, B0); PG8_BAR; PG8_SCHED;
;             PG8_STAGE(PG8_SB(0, 1), b2 + hstepB, voffB);
;             PG8_WAIT_V(6); PG8_BAR; PG8_MMA(1, 1, At, B1); PG8_BAR;
.LBB0_910:
	s_add_i32 s83, s54, 2
	s_add_u32 s55, s46, 0xffea0080
	s_addc_u32 s56, s47, -1
	s_cmp_eq_u32 s18, s54
	s_cselect_b32 s54, s0, s41
	s_cselect_b32 s57, s45, s56
	s_cselect_b32 s56, s44, s55
	s_cselect_b32 s55, s1, s82
	ds_read_b128 v[150:153], v170
	ds_read_b128 v[154:157], v170 offset:1024
	ds_read_b128 v[174:177], v170 offset:2048
	ds_read_b128 v[178:181], v170 offset:3072
	ds_read_b128 v[182:185], v171
	ds_read_b128 v[186:189], v171 offset:1024
	ds_read_b128 v[190:193], v171 offset:2048
	ds_read_b128 v[194:197], v171 offset:3072
	ds_read_b128 v[198:201], v171 offset:4096
	ds_read_b128 v[202:205], v171 offset:5120
	ds_read_b128 v[206:209], v171 offset:6144
	ds_read_b128 v[210:213], v171 offset:7168
	ds_read_b128 v[214:217], v172
	ds_read_b128 v[218:221], v172 offset:1024
	ds_read_b128 v[222:225], v172 offset:2048
	ds_read_b128 v[226:229], v172 offset:3072
	s_add_i32 m0, s33, 0xc000
	v_lshl_add_u64 v[158:159], s[46:47], 0, v[144:145]
	global_load_lds_dwordx4 v[158:159], off
	s_add_i32 m0, s33, 0xe000
	v_lshl_add_u64 v[158:159], s[46:47], 0, v[146:147]
	global_load_lds_dwordx4 v[158:159], off
	s_waitcnt vmcnt(8) lgkmcnt(0)
	s_barrier
	v_mfma_f32_16x16x32_bf16 v[124:127], v[150:153], v[182:185], v[124:127]
	v_mfma_f32_16x16x32_bf16 v[120:123], v[174:177], v[182:185], v[120:123]
	v_mfma_f32_16x16x32_bf16 v[116:119], v[150:153], v[190:193], v[116:119]
	v_mfma_f32_16x16x32_bf16 v[108:111], v[174:177], v[190:193], v[108:111]
	v_mfma_f32_16x16x32_bf16 v[100:103], v[150:153], v[198:201], v[100:103]
	v_mfma_f32_16x16x32_bf16 v[92:95], v[174:177], v[198:201], v[92:95]
	v_mfma_f32_16x16x32_bf16 v[84:87], v[150:153], v[206:209], v[84:87]
	v_mfma_f32_16x16x32_bf16 v[76:79], v[174:177], v[206:209], v[76:79]
	v_mfma_f32_16x16x32_bf16 v[124:127], v[154:157], v[186:189], v[124:127]
	v_mfma_f32_16x16x32_bf16 v[120:123], v[178:181], v[186:189], v[120:123]
	v_mfma_f32_16x16x32_bf16 v[116:119], v[154:157], v[194:197], v[116:119]
	v_mfma_f32_16x16x32_bf16 v[108:111], v[178:181], v[194:197], v[108:111]
	v_mfma_f32_16x16x32_bf16 v[100:103], v[154:157], v[202:205], v[100:103]
	v_mfma_f32_16x16x32_bf16 v[92:95], v[178:181], v[202:205], v[92:95]
	v_mfma_f32_16x16x32_bf16 v[84:87], v[154:157], v[210:213], v[84:87]
	v_mfma_f32_16x16x32_bf16 v[76:79], v[178:181], v[210:213], v[76:79]
	v_mfma_f32_16x16x32_bf16 v[112:115], v[214:217], v[182:185], v[112:115]
	v_mfma_f32_16x16x32_bf16 v[104:107], v[222:225], v[182:185], v[104:107]
	v_mfma_f32_16x16x32_bf16 v[96:99], v[214:217], v[190:193], v[96:99]
	v_mfma_f32_16x16x32_bf16 v[88:91], v[222:225], v[190:193], v[88:91]
	v_mfma_f32_16x16x32_bf16 v[80:83], v[214:217], v[198:201], v[80:83]
	v_mfma_f32_16x16x32_bf16 v[72:75], v[222:225], v[198:201], v[72:75]
	v_mfma_f32_16x16x32_bf16 v[68:71], v[214:217], v[206:209], v[68:71]
	v_mfma_f32_16x16x32_bf16 v[64:67], v[222:225], v[206:209], v[64:67]
	v_mfma_f32_16x16x32_bf16 v[112:115], v[218:221], v[186:189], v[112:115]
	v_mfma_f32_16x16x32_bf16 v[104:107], v[226:229], v[186:189], v[104:107]
	v_mfma_f32_16x16x32_bf16 v[96:99], v[218:221], v[194:197], v[96:99]
	v_mfma_f32_16x16x32_bf16 v[88:91], v[226:229], v[194:197], v[88:91]
	v_mfma_f32_16x16x32_bf16 v[80:83], v[218:221], v[202:205], v[80:83]
	v_mfma_f32_16x16x32_bf16 v[72:75], v[226:229], v[202:205], v[72:75]
	v_mfma_f32_16x16x32_bf16 v[68:71], v[218:221], v[210:213], v[68:71]
	v_mfma_f32_16x16x32_bf16 v[64:67], v[226:229], v[210:213], v[64:67]
	s_barrier
	ds_read_b128 v[182:185], v171 offset:16384
	ds_read_b128 v[186:189], v171 offset:17408
	ds_read_b128 v[190:193], v171 offset:18432
	ds_read_b128 v[194:197], v171 offset:19456
	ds_read_b128 v[198:201], v171 offset:20480
	ds_read_b128 v[202:205], v171 offset:21504
	ds_read_b128 v[206:209], v171 offset:22528
	ds_read_b128 v[210:213], v171 offset:23552
	s_add_i32 s84, s65, s21
	s_mov_b32 m0, s84
	v_lshl_add_u64 v[158:159], s[54:55], 0, v[138:139]
	global_load_lds_dwordx4 v[158:159], off
	s_add_i32 m0, s84, 0x2000
	v_lshl_add_u64 v[230:231], s[54:55], 0, v[142:143]
	global_load_lds_dwordx4 v[230:231], off
	s_mov_b32 m0, s33
	v_lshl_add_u64 v[232:233], s[56:57], 0, v[136:137]
	global_load_lds_dwordx4 v[232:233], off
	s_mov_b32 m0, s35
	v_lshl_add_u64 v[234:235], s[56:57], 0, v[140:141]
	global_load_lds_dwordx4 v[234:235], off
	s_add_u32 s84, s54, 0xb0000
	s_addc_u32 s85, s55, 0
	s_add_i32 s86, s66, s21
	s_mov_b32 m0, s86
	v_lshl_add_u64 v[240:241], s[84:85], 0, v[138:139]
	global_load_lds_dwordx4 v[240:241], off
	s_add_i32 m0, s86, 0x2000
	v_lshl_add_u64 v[240:241], s[84:85], 0, v[142:143]
	global_load_lds_dwordx4 v[240:241], off
	s_waitcnt vmcnt(8) lgkmcnt(0)
	s_barrier
; #define PG8_STAGE(bufoff, gbase, voff) do { _Pragma("unroll") for (int _i = 0; _i < 2; ++_i) \
;         __builtin_amdgcn_global_load_lds((const unsigned*)((const char*)(gbase) + (voff)[_i]), (LAS unsigned*)(lds + (bufoff) + ldsw + _i * 8192), 16, 0, 0); } while (0)
; #define PG8_LDA(dst, b, h) do { _Pragma("unroll") for (int m = 0; m < 4; ++m) _Pragma("unroll") for (int k = 0; k < 2; ++k) dst[m][k] = *(const LAS bf16x8*)(lds + PG8_SA(b, h) + aoff + m * 2048 + k * 1024); } while (0)
; #define PG8_LDB(dst, b, h) do { _Pragma("unroll") for (int n = 0; n < 2; ++n) _Pragma("unroll") for (int k = 0; k < 2; ++k) dst[n][k] = *(const LAS bf16x8*)(lds + PG8_SB(b, h) + boff + n * 2048 + k * 1024); } while (0)
; #define PG8_MMA(ai, bj, At, Bt) do { __builtin_amdgcn_s_setprio(1); _Pragma("unroll") for (int m = 0; m < 4; ++m) _Pragma("unroll") for (int n = 0; n < 2; ++n) _Pragma("unroll") for (int k = 0; k < 2; ++k) \
;         acc[ai][bj][m][n] = __builtin_amdgcn_mfma_f32_16x16x32_bf16(Bt[n][k], At[m][k], acc[ai][bj][m][n], 0, 0, 0); __builtin_amdgcn_s_setprio(0); } while (0)
; #define PG8_WAIT_V(n) asm volatile("s_waitcnt vmcnt(" #n ")" ::: "memory")
; #define PG8_WAIT_L(n) asm volatile("s_waitcnt lgkmcnt(" #n ")" ::: "memory")
; #define PG8_BAR __builtin_amdgcn_s_barrier()
; #define PG8_SCHED __builtin_amdgcn_sched_barrier(0)
; template <class Epi>
; __device__ __forceinline__ void gemm_phase(LAS unsigned char* lds, const Gemm g, const StaticOrder& S, const Epi& E) {
;     ...
;             PG8_WAIT_V(6); PG8_BAR; PG8_MMA(1, 1, At, B1); PG8_BAR;
;             PG8_LDB(B0, 1, 0); PG8_SCHED; PG8_LDA(At, 1, 0); PG8_STAGE(PG8_SA(0, 1), a2 + hstepA, voffA);
;             PG8_WAIT_L(8); PG8_BAR; PG8_WAIT_L(0); PG8_MMA(0, 0, At, B0); PG8_BAR; PG8_SCHED;
;             PG8_LDB(B1, 1, 1); PG8_STAGE(PG8_SB(1, 0), b3, voffB);
;             PG8_BAR; PG8_WAIT_L(0); PG8_MMA(0, 1, At, B1); PG8_BAR;
;             PG8_LDA(At, 1, 1); PG8_STAGE(PG8_SA(1, 0), a3, voffA);
;             PG8_BAR; PG8_WAIT_L(0); PG8_MMA(1, 0, At, B0); PG8_BAR; PG8_SCHED;
	v_mfma_f32_16x16x32_bf16 v[60:63], v[150:153], v[182:185], v[60:63]
	v_mfma_f32_16x16x32_bf16 v[56:59], v[174:177], v[182:185], v[56:59]
	v_mfma_f32_16x16x32_bf16 v[52:55], v[150:153], v[190:193], v[52:55]
	v_mfma_f32_16x16x32_bf16 v[44:47], v[174:177], v[190:193], v[44:47]
	v_mfma_f32_16x16x32_bf16 v[36:39], v[150:153], v[198:201], v[36:39]
	v_mfma_f32_16x16x32_bf16 v[28:31], v[174:177], v[198:201], v[28:31]
	v_mfma_f32_16x16x32_bf16 v[20:23], v[150:153], v[206:209], v[20:23]
	v_mfma_f32_16x16x32_bf16 v[12:15], v[174:177], v[206:209], v[12:15]
	v_mfma_f32_16x16x32_bf16 v[60:63], v[154:157], v[186:189], v[60:63]
	v_mfma_f32_16x16x32_bf16 v[56:59], v[178:181], v[186:189], v[56:59]
	v_mfma_f32_16x16x32_bf16 v[52:55], v[154:157], v[194:197], v[52:55]
	v_mfma_f32_16x16x32_bf16 v[44:47], v[178:181], v[194:197], v[44:47]
	v_mfma_f32_16x16x32_bf16 v[36:39], v[154:157], v[202:205], v[36:39]
	v_mfma_f32_16x16x32_bf16 v[28:31], v[178:181], v[202:205], v[28:31]
	v_mfma_f32_16x16x32_bf16 v[20:23], v[154:157], v[210:213], v[20:23]
	v_mfma_f32_16x16x32_bf16 v[12:15], v[178:181], v[210:213], v[12:15]
	v_mfma_f32_16x16x32_bf16 v[48:51], v[214:217], v[182:185], v[48:51]
	v_mfma_f32_16x16x32_bf16 v[40:43], v[222:225], v[182:185], v[40:43]
	v_mfma_f32_16x16x32_bf16 v[32:35], v[214:217], v[190:193], v[32:35]
	v_mfma_f32_16x16x32_bf16 v[24:27], v[222:225], v[190:193], v[24:27]
	v_mfma_f32_16x16x32_bf16 v[16:19], v[214:217], v[198:201], v[16:19]
	v_mfma_f32_16x16x32_bf16 v[8:11], v[222:225], v[198:201], v[8:11]
	v_mfma_f32_16x16x32_bf16 v[4:7], v[214:217], v[206:209], v[4:7]
	v_mfma_f32_16x16x32_bf16 v[0:3], v[222:225], v[206:209], v[0:3]
	v_mfma_f32_16x16x32_bf16 v[48:51], v[218:221], v[186:189], v[48:51]
	v_mfma_f32_16x16x32_bf16 v[40:43], v[226:229], v[186:189], v[40:43]
	v_mfma_f32_16x16x32_bf16 v[32:35], v[218:221], v[194:197], v[32:35]
	v_mfma_f32_16x16x32_bf16 v[24:27], v[226:229], v[194:197], v[24:27]
	v_mfma_f32_16x16x32_bf16 v[16:19], v[218:221], v[202:205], v[16:19]
	v_mfma_f32_16x16x32_bf16 v[8:11], v[226:229], v[202:205], v[8:11]
	v_mfma_f32_16x16x32_bf16 v[4:7], v[218:221], v[210:213], v[4:7]
	v_mfma_f32_16x16x32_bf16 v[0:3], v[226:229], v[210:213], v[0:3]
	s_barrier
	s_add_i32 s84, 0, 0x18000
	v_add_u32_e32 v173, s84, v168
	ds_read_b128 v[150:153], v173
	ds_read_b128 v[154:157], v173 offset:1024
	ds_read_b128 v[174:177], v173 offset:2048
	ds_read_b128 v[178:181], v173 offset:3072
	ds_read_b128 v[182:185], v171 offset:32768
	ds_read_b128 v[186:189], v171 offset:33792
	ds_read_b128 v[190:193], v171 offset:34816
	ds_read_b128 v[194:197], v171 offset:35840
	ds_read_b128 v[198:201], v171 offset:36864
	ds_read_b128 v[202:205], v171 offset:37888
	ds_read_b128 v[206:209], v171 offset:38912
	ds_read_b128 v[210:213], v171 offset:39936
	s_add_i32 s98, 0, 0x1c000
	v_add_u32_e32 v246, s98, v168
	ds_read_b128 v[214:217], v246
	ds_read_b128 v[218:221], v246 offset:1024
	ds_read_b128 v[222:225], v246 offset:2048
	ds_read_b128 v[226:229], v246 offset:3072
	s_add_u32 s56, s56, 0x160000
	s_addc_u32 s57, s57, 0
	s_mov_b32 m0, s58
	v_lshl_add_u64 v[244:245], s[56:57], 0, v[136:137]
	global_load_lds_dwordx4 v[244:245], off
	s_mov_b32 m0, s59
	v_lshl_add_u64 v[244:245], s[56:57], 0, v[140:141]
	global_load_lds_dwordx4 v[244:245], off
	s_waitcnt vmcnt(8) lgkmcnt(0)
	s_barrier
	v_mfma_f32_16x16x32_bf16 v[124:127], v[150:153], v[182:185], v[124:127]
	v_mfma_f32_16x16x32_bf16 v[120:123], v[174:177], v[182:185], v[120:123]
	v_mfma_f32_16x16x32_bf16 v[116:119], v[150:153], v[190:193], v[116:119]
	v_mfma_f32_16x16x32_bf16 v[108:111], v[174:177], v[190:193], v[108:111]
	v_mfma_f32_16x16x32_bf16 v[100:103], v[150:153], v[198:201], v[100:103]
	v_mfma_f32_16x16x32_bf16 v[92:95], v[174:177], v[198:201], v[92:95]
	v_mfma_f32_16x16x32_bf16 v[84:87], v[150:153], v[206:209], v[84:87]
	v_mfma_f32_16x16x32_bf16 v[76:79], v[174:177], v[206:209], v[76:79]
	v_mfma_f32_16x16x32_bf16 v[124:127], v[154:157], v[186:189], v[124:127]
	v_mfma_f32_16x16x32_bf16 v[120:123], v[178:181], v[186:189], v[120:123]
	v_mfma_f32_16x16x32_bf16 v[116:119], v[154:157], v[194:197], v[116:119]
	v_mfma_f32_16x16x32_bf16 v[108:111], v[178:181], v[194:197], v[108:111]
	v_mfma_f32_16x16x32_bf16 v[100:103], v[154:157], v[202:205], v[100:103]
	v_mfma_f32_16x16x32_bf16 v[92:95], v[178:181], v[202:205], v[92:95]
	v_mfma_f32_16x16x32_bf16 v[84:87], v[154:157], v[210:213], v[84:87]
	v_mfma_f32_16x16x32_bf16 v[76:79], v[178:181], v[210:213], v[76:79]
	v_mfma_f32_16x16x32_bf16 v[112:115], v[214:217], v[182:185], v[112:115]
	v_mfma_f32_16x16x32_bf16 v[104:107], v[222:225], v[182:185], v[104:107]
	v_mfma_f32_16x16x32_bf16 v[96:99], v[214:217], v[190:193], v[96:99]
	v_mfma_f32_16x16x32_bf16 v[88:91], v[222:225], v[190:193], v[88:91]
	v_mfma_f32_16x16x32_bf16 v[80:83], v[214:217], v[198:201], v[80:83]
	v_mfma_f32_16x16x32_bf16 v[72:75], v[222:225], v[198:201], v[72:75]
	v_mfma_f32_16x16x32_bf16 v[68:71], v[214:217], v[206:209], v[68:71]
	v_mfma_f32_16x16x32_bf16 v[64:67], v[222:225], v[206:209], v[64:67]
	v_mfma_f32_16x16x32_bf16 v[112:115], v[218:221], v[186:189], v[112:115]
	v_mfma_f32_16x16x32_bf16 v[104:107], v[226:229], v[186:189], v[104:107]
	v_mfma_f32_16x16x32_bf16 v[96:99], v[218:221], v[194:197], v[96:99]
	v_mfma_f32_16x16x32_bf16 v[88:91], v[226:229], v[194:197], v[88:91]
	v_mfma_f32_16x16x32_bf16 v[80:83], v[218:221], v[202:205], v[80:83]
	v_mfma_f32_16x16x32_bf16 v[72:75], v[226:229], v[202:205], v[72:75]
	v_mfma_f32_16x16x32_bf16 v[68:71], v[218:221], v[210:213], v[68:71]
	v_mfma_f32_16x16x32_bf16 v[64:67], v[226:229], v[210:213], v[64:67]
	s_barrier
; #define PG8_STAGE(bufoff, gbase, voff) do { _Pragma("unroll") for (int _i = 0; _i < 2; ++_i) \
;         __builtin_amdgcn_global_load_lds((const unsigned*)((const char*)(gbase) + (voff)[_i]), (LAS unsigned*)(lds + (bufoff) + ldsw + _i * 8192), 16, 0, 0); } while (0)
; #define PG8_LDA(dst, b, h) do { _Pragma("unroll") for (int m = 0; m < 4; ++m) _Pragma("unroll") for (int k = 0; k < 2; ++k) dst[m][k] = *(const LAS bf16x8*)(lds + PG8_SA(b, h) + aoff + m * 2048 + k * 1024); } while (0)
; #define PG8_MMA(ai, bj, At, Bt) do { __builtin_amdgcn_s_setprio(1); _Pragma("unroll") for (int m = 0; m < 4; ++m) _Pragma("unroll") for (int n = 0; n < 2; ++n) _Pragma("unroll") for (int k = 0; k < 2; ++k) \
;         acc[ai][bj][m][n] = __builtin_amdgcn_mfma_f32_16x16x32_bf16(Bt[n][k], At[m][k], acc[ai][bj][m][n], 0, 0, 0); __builtin_amdgcn_s_setprio(0); } while (0)
; #define PG8_WAIT_V(n) asm volatile("s_waitcnt vmcnt(" #n ")" ::: "memory")
; #define PG8_WAIT_L(n) asm volatile("s_waitcnt lgkmcnt(" #n ")" ::: "memory")
; #define PG8_BAR __builtin_amdgcn_s_barrier()
; #define PG8_SCHED __builtin_amdgcn_sched_barrier(0)
; template <class Epi>
; __device__ __forceinline__ void gemm_phase(LAS unsigned char* lds, const Gemm g, const StaticOrder& S, const Epi& E) {
;     ...
;             PG8_LDA(At, 1, 1); PG8_STAGE(PG8_SA(1, 0), a3, voffA);
;             PG8_BAR; PG8_WAIT_L(0); PG8_MMA(1, 0, At, B0); PG8_BAR; PG8_SCHED;
;             PG8_STAGE(PG8_SB(1, 1), b3 + hstepB, voffB);
;             PG8_WAIT_V(6); PG8_BAR; PG8_MMA(1, 1, At, B1); PG8_BAR;
;         }
	ds_read_b128 v[182:185], v171 offset:49152
	ds_read_b128 v[186:189], v171 offset:50176
	ds_read_b128 v[190:193], v171 offset:51200
	ds_read_b128 v[194:197], v171 offset:52224
	ds_read_b128 v[198:201], v171 offset:53248
	ds_read_b128 v[202:205], v171 offset:54272
	ds_read_b128 v[206:209], v171 offset:55296
	ds_read_b128 v[210:213], v171 offset:56320
	s_add_i32 s57, s84, s21
	s_mov_b32 m0, s57
	v_lshl_add_u64 v[158:159], v[158:159], 0, s[22:23]
	global_load_lds_dwordx4 v[158:159], off
	s_add_i32 m0, s57, 0x2000
	v_lshl_add_u64 v[158:159], v[230:231], 0, s[22:23]
	global_load_lds_dwordx4 v[158:159], off
	s_mov_b32 m0, s60
	v_lshl_add_u64 v[158:159], v[232:233], 0, s[22:23]
	global_load_lds_dwordx4 v[158:159], off
	s_mov_b32 m0, s61
	v_lshl_add_u64 v[158:159], v[234:235], 0, s[22:23]
	global_load_lds_dwordx4 v[158:159], off
	s_add_u32 s54, s54, 0xb0080
	s_addc_u32 s55, s55, 0
	s_add_i32 s56, s98, s21
	s_mov_b32 m0, s56
	v_lshl_add_u64 v[240:241], s[54:55], 0, v[138:139]
	global_load_lds_dwordx4 v[240:241], off
	s_add_i32 m0, s56, 0x2000
	v_lshl_add_u64 v[240:241], s[54:55], 0, v[142:143]
	global_load_lds_dwordx4 v[240:241], off
	s_waitcnt vmcnt(8) lgkmcnt(0)
	s_barrier
	v_mfma_f32_16x16x32_bf16 v[60:63], v[150:153], v[182:185], v[60:63]
	v_mfma_f32_16x16x32_bf16 v[56:59], v[174:177], v[182:185], v[56:59]
	v_mfma_f32_16x16x32_bf16 v[52:55], v[150:153], v[190:193], v[52:55]
	v_mfma_f32_16x16x32_bf16 v[44:47], v[174:177], v[190:193], v[44:47]
	v_mfma_f32_16x16x32_bf16 v[36:39], v[150:153], v[198:201], v[36:39]
	v_mfma_f32_16x16x32_bf16 v[28:31], v[174:177], v[198:201], v[28:31]
	v_mfma_f32_16x16x32_bf16 v[20:23], v[150:153], v[206:209], v[20:23]
	v_mfma_f32_16x16x32_bf16 v[12:15], v[174:177], v[206:209], v[12:15]
	v_mfma_f32_16x16x32_bf16 v[60:63], v[154:157], v[186:189], v[60:63]
	v_mfma_f32_16x16x32_bf16 v[56:59], v[178:181], v[186:189], v[56:59]
	v_mfma_f32_16x16x32_bf16 v[52:55], v[154:157], v[194:197], v[52:55]
	v_mfma_f32_16x16x32_bf16 v[44:47], v[178:181], v[194:197], v[44:47]
	v_mfma_f32_16x16x32_bf16 v[36:39], v[154:157], v[202:205], v[36:39]
	v_mfma_f32_16x16x32_bf16 v[28:31], v[178:181], v[202:205], v[28:31]
	v_mfma_f32_16x16x32_bf16 v[20:23], v[154:157], v[210:213], v[20:23]
	v_mfma_f32_16x16x32_bf16 v[12:15], v[178:181], v[210:213], v[12:15]
	v_mfma_f32_16x16x32_bf16 v[48:51], v[214:217], v[182:185], v[48:51]
	v_mfma_f32_16x16x32_bf16 v[40:43], v[222:225], v[182:185], v[40:43]
	v_mfma_f32_16x16x32_bf16 v[32:35], v[214:217], v[190:193], v[32:35]
	v_mfma_f32_16x16x32_bf16 v[24:27], v[222:225], v[190:193], v[24:27]
	v_mfma_f32_16x16x32_bf16 v[16:19], v[214:217], v[198:201], v[16:19]
	v_mfma_f32_16x16x32_bf16 v[8:11], v[222:225], v[198:201], v[8:11]
	v_mfma_f32_16x16x32_bf16 v[4:7], v[214:217], v[206:209], v[4:7]
	v_mfma_f32_16x16x32_bf16 v[0:3], v[222:225], v[206:209], v[0:3]
	v_mfma_f32_16x16x32_bf16 v[48:51], v[218:221], v[186:189], v[48:51]
	v_mfma_f32_16x16x32_bf16 v[40:43], v[226:229], v[186:189], v[40:43]
	v_mfma_f32_16x16x32_bf16 v[32:35], v[218:221], v[194:197], v[32:35]
	v_mfma_f32_16x16x32_bf16 v[24:27], v[226:229], v[194:197], v[24:27]
	v_mfma_f32_16x16x32_bf16 v[16:19], v[218:221], v[202:205], v[16:19]
	v_mfma_f32_16x16x32_bf16 v[8:11], v[226:229], v[202:205], v[8:11]
	v_mfma_f32_16x16x32_bf16 v[4:7], v[218:221], v[210:213], v[4:7]
	v_mfma_f32_16x16x32_bf16 v[0:3], v[226:229], v[210:213], v[0:3]
	s_add_u32 s46, s46, 0x100
	s_addc_u32 s47, s47, 0
	s_add_u32 s41, s41, 0x100
	s_addc_u32 s82, s82, 0
	s_cmp_ge_i32 s83, s81
	s_mov_b32 s54, s83
	s_cbranch_scc1 .Leo_exit3
	s_barrier
	s_branch .LBB0_910

;     __device__ __forceinline__ void operator()(const f32x4 (&acc)[2][2][4][2], const Unit& u, int wr, int wc, int fr, int fq) const {
;         const int row0 = u.pm * BM + wr * 64 + fr, col0 = u.pn * BM + wc * 32 + 8 * fq;
;         if (u.part) {
;             float* base = tailacc + (size_t)(u.part - 1) * slab - (size_t)tail_row0 * tail_ld;
; #pragma unroll
;             for (int ai = 0; ai < 2; ++ai)
; #pragma unroll
;                 for (int m = 0; m < 4; ++m) { float* rowp = base + (size_t)(row0 + ai * HALF + m * 16) * tail_ld + col0;
; #pragma unroll
;                     for (int bj = 0; bj < 2; ++bj)
; #pragma unroll
;                         for (int n = 0; n < 2; ++n) *(f32x4*)(rowp + bj * HALF + 4 * n) = acc[ai][bj][m][n]; }
;             return;
.Leo_b3:
	v_lshl_add_u32 v158, s78, 8, v167
	v_lshl_or_b32 v150, s79, 8, v169
	v_or_b32_e32 v156, 16, v158
	v_or_b32_e32 v154, 32, v158
	v_or_b32_e32 v152, 48, v158
	s_cmp_lg_u32 s80, 0
	v_ashrrev_i32_e32 v151, 31, v150
	v_ashrrev_i32_e32 v159, 31, v158
	v_ashrrev_i32_e32 v157, 31, v156
	v_ashrrev_i32_e32 v155, 31, v154
	v_ashrrev_i32_e32 v153, 31, v152
	s_cbranch_scc0 .LBB0_913
	s_add_i32 s18, s80, -1
	s_lshl_b64 s[46:47], s[18:19], 21
	s_add_u32 s46, s92, s46
	s_addc_u32 s47, s93, s47
	v_lshl_add_u64 v[174:175], v[150:151], 2, s[46:47]
	s_brev_b32 s46, 63
	s_mov_b32 s47, -1
	v_lshl_add_u64 v[174:175], v[174:175], 0, s[46:47]
	v_lshlrev_b64 v[176:177], 12, v[158:159]
	v_lshlrev_b64 v[178:179], 12, v[156:157]
	v_lshl_add_u64 v[176:177], v[174:175], 0, v[176:177]
	v_lshl_add_u64 v[178:179], v[174:175], 0, v[178:179]
	global_store_dwordx4 v[176:177], v[124:127], off
	global_store_dwordx4 v[176:177], v[120:123], off offset:16
	global_store_dwordx4 v[176:177], v[112:115], off offset:512
	global_store_dwordx4 v[176:177], v[104:107], off offset:528
	global_store_dwordx4 v[178:179], v[116:119], off
	global_store_dwordx4 v[178:179], v[108:111], off offset:16
	global_store_dwordx4 v[178:179], v[96:99], off offset:512
	global_store_dwordx4 v[178:179], v[88:91], off offset:528
	v_lshlrev_b64 v[178:179], 12, v[154:155]
	v_lshl_add_u64 v[178:179], v[174:175], 0, v[178:179]
	global_store_dwordx4 v[178:179], v[100:103], off
	global_store_dwordx4 v[178:179], v[92:95], off offset:16
	global_store_dwordx4 v[178:179], v[80:83], off offset:512
	global_store_dwordx4 v[178:179], v[72:75], off offset:528
	v_lshlrev_b64 v[178:179], 12, v[152:153]
	s_mov_b32 s18, 0x80000
	v_lshl_add_u64 v[174:175], v[174:175], 0, v[178:179]
	v_add_co_u32_e32 v178, vcc, s18, v176
	s_mov_b64 s[46:47], 0x80000
	s_nop 0
	v_addc_co_u32_e32 v179, vcc, 0, v177, vcc
	global_store_dwordx4 v[174:175], v[84:87], off
	global_store_dwordx4 v[174:175], v[76:79], off offset:16
	global_store_dwordx4 v[174:175], v[68:71], off offset:512
	global_store_dwordx4 v[174:175], v[64:67], off offset:528
	v_lshl_add_u64 v[174:175], v[176:177], 0, s[46:47]
	global_store_dwordx4 v[178:179], v[60:63], off
	global_store_dwordx4 v[174:175], v[56:59], off offset:16
	global_store_dwordx4 v[174:175], v[48:51], off offset:512
	global_store_dwordx4 v[174:175], v[40:43], off offset:528
	v_add_co_u32_e32 v178, vcc, s67, v176
	s_mov_b64 s[46:47], 0x90000
	s_nop 0
	v_addc_co_u32_e32 v179, vcc, 0, v177, vcc
	v_lshl_add_u64 v[174:175], v[176:177], 0, s[46:47]
	global_store_dwordx4 v[178:179], v[52:55], off
	global_store_dwordx4 v[174:175], v[44:47], off offset:16
	global_store_dwordx4 v[174:175], v[32:35], off offset:512
	global_store_dwordx4 v[174:175], v[24:27], off offset:528
	v_add_co_u32_e32 v178, vcc, s68, v176
	v_lshl_add_u64 v[174:175], v[176:177], 0, s[24:25]
	s_nop 0
	v_addc_co_u32_e32 v179, vcc, 0, v177, vcc
	s_mov_b64 s[46:47], 0xb0000
	global_store_dwordx4 v[178:179], v[36:39], off
	global_store_dwordx4 v[174:175], v[28:31], off offset:16
	global_store_dwordx4 v[174:175], v[16:19], off offset:512
	global_store_dwordx4 v[174:175], v[8:11], off offset:528
	v_lshl_add_u64 v[174:175], v[176:177], 0, s[46:47]
	v_add_co_u32_e32 v176, vcc, 0xb0000, v176
	s_nop 1
	v_addc_co_u32_e32 v177, vcc, 0, v177, vcc
	global_store_dwordx4 v[176:177], v[20:23], off
	global_store_dwordx4 v[174:175], v[12:15], off offset:16
	global_store_dwordx4 v[174:175], v[4:7], off offset:512
	global_store_dwordx4 v[174:175], v[0:3], off offset:528
	s_cbranch_execnz .LBB0_895
	s_branch .LBB0_894

; #define PG8_STAGE(bufoff, gbase, voff) do { _Pragma("unroll") for (int _i = 0; _i < 2; ++_i) \
;         __builtin_amdgcn_global_load_lds((const unsigned*)((const char*)(gbase) + (voff)[_i]), (LAS unsigned*)(lds + (bufoff) + ldsw + _i * 8192), 16, 0, 0); } while (0)
; #define PG8_LDA(dst, b, h) do { _Pragma("unroll") for (int m = 0; m < 4; ++m) _Pragma("unroll") for (int k = 0; k < 2; ++k) dst[m][k] = *(const LAS bf16x8*)(lds + PG8_SA(b, h) + aoff + m * 2048 + k * 1024); } while (0)
; #define PG8_LDB(dst, b, h) do { _Pragma("unroll") for (int n = 0; n < 2; ++n) _Pragma("unroll") for (int k = 0; k < 2; ++k) dst[n][k] = *(const LAS bf16x8*)(lds + PG8_SB(b, h) + boff + n * 2048 + k * 1024); } while (0)
; #define PG8_MMA(ai, bj, At, Bt) do { __builtin_amdgcn_s_setprio(1); _Pragma("unroll") for (int m = 0; m < 4; ++m) _Pragma("unroll") for (int n = 0; n < 2; ++n) _Pragma("unroll") for (int k = 0; k < 2; ++k) \
;         acc[ai][bj][m][n] = __builtin_amdgcn_mfma_f32_16x16x32_bf16(Bt[n][k], At[m][k], acc[ai][bj][m][n], 0, 0, 0); __builtin_amdgcn_s_setprio(0); } while (0)
; #define PG8_WAIT_V(n) asm volatile("s_waitcnt vmcnt(" #n ")" ::: "memory")
; #define PG8_WAIT_L(n) asm volatile("s_waitcnt lgkmcnt(" #n ")" ::: "memory")
; template <class Epi>
; __device__ __forceinline__ void gemm_phase(LAS unsigned char* lds, const Gemm g, const StaticOrder& S, const Epi& E) {
;     ...
;         for (int t = 0; t < nt; t += 2) {
;             const bool last = (t == nt - 2);
;             const char* a1 = cA + (size_t)(t + 1) * kstep;
;             const char* a2 = last ? nA : cA + (size_t)(t + 2) * kstep; const char* b2 = last ? nB : cB + (size_t)(t + 2) * kstep;
;             const char* a3 = a2 + kstep; const char* b3 = b2 + kstep;
;             PG8_LDB(B0, 0, 0); PG8_SCHED; PG8_LDA(At, 0, 0); PG8_STAGE(PG8_SA(1, 1), a1 + hstepA, voffA);
;             PG8_WAIT_L(8); PG8_BAR; PG8_WAIT_L(0); PG8_MMA(0, 0, At, B0); PG8_BAR; PG8_SCHED;
;             PG8_LDB(B1, 0, 1); PG8_STAGE(PG8_SB(0, 0), b2, voffB);
;             PG8_BAR; PG8_WAIT_L(0); PG8_MMA(0, 1, At, B1); PG8_BAR;
;             PG8_LDA(At, 0, 1); PG8_STAGE(PG8_SA(0, 0), a2, voffA);
;             PG8_BAR; PG8_WAIT_L(0); PG8_MMA(1, 0, At, B0); PG8_BAR; PG8_SCHED;
;             PG8_STAGE(PG8_SB(0, 1), b2 + hstepB, voffB);
;             PG8_WAIT_V(6); PG8_BAR; PG8_MMA(1, 1, At, B1); PG8_BAR;
.LBB0_1146:
	s_add_i32 s77, s45, 2
	s_add_u32 s54, s50, 0xfffc0080
	s_addc_u32 s55, s51, -1
	s_cmp_eq_u32 s39, s45
	s_cselect_b32 s57, s49, s55
	s_cselect_b32 s56, s48, s54
	s_cselect_b32 s55, s1, s43
	s_cselect_b32 s54, s0, s41
	ds_read_b128 v[150:153], v129
	ds_read_b128 v[154:157], v129 offset:1024
	ds_read_b128 v[158:161], v129 offset:2048
	ds_read_b128 v[166:169], v129 offset:3072
	ds_read_b128 v[170:173], v163
	ds_read_b128 v[174:177], v163 offset:1024
	ds_read_b128 v[178:181], v163 offset:2048
	ds_read_b128 v[182:185], v163 offset:3072
	ds_read_b128 v[186:189], v163 offset:4096
	ds_read_b128 v[190:193], v163 offset:5120
	ds_read_b128 v[194:197], v163 offset:6144
	ds_read_b128 v[198:201], v163 offset:7168
	ds_read_b128 v[202:205], v164
	ds_read_b128 v[206:209], v164 offset:1024
	ds_read_b128 v[210:213], v164 offset:2048
	ds_read_b128 v[214:217], v164 offset:3072
	s_add_i32 m0, s33, 0xc000
	v_lshl_add_u64 v[242:243], s[50:51], 0, v[144:145]
	global_load_lds_dwordx4 v[242:243], off
	s_add_i32 m0, s33, 0xe000
	v_lshl_add_u64 v[242:243], s[50:51], 0, v[146:147]
	global_load_lds_dwordx4 v[242:243], off
	s_waitcnt vmcnt(8) lgkmcnt(0)
	s_barrier
	v_mfma_f32_16x16x32_bf16 v[124:127], v[150:153], v[170:173], v[124:127]
	v_mfma_f32_16x16x32_bf16 v[120:123], v[158:161], v[170:173], v[120:123]
	v_mfma_f32_16x16x32_bf16 v[116:119], v[150:153], v[178:181], v[116:119]
	v_mfma_f32_16x16x32_bf16 v[108:111], v[158:161], v[178:181], v[108:111]
	v_mfma_f32_16x16x32_bf16 v[100:103], v[150:153], v[186:189], v[100:103]
	v_mfma_f32_16x16x32_bf16 v[92:95], v[158:161], v[186:189], v[92:95]
	v_mfma_f32_16x16x32_bf16 v[84:87], v[150:153], v[194:197], v[84:87]
	v_mfma_f32_16x16x32_bf16 v[76:79], v[158:161], v[194:197], v[76:79]
	v_mfma_f32_16x16x32_bf16 v[124:127], v[154:157], v[174:177], v[124:127]
	v_mfma_f32_16x16x32_bf16 v[120:123], v[166:169], v[174:177], v[120:123]
	v_mfma_f32_16x16x32_bf16 v[116:119], v[154:157], v[182:185], v[116:119]
	v_mfma_f32_16x16x32_bf16 v[108:111], v[166:169], v[182:185], v[108:111]
	v_mfma_f32_16x16x32_bf16 v[100:103], v[154:157], v[190:193], v[100:103]
	v_mfma_f32_16x16x32_bf16 v[92:95], v[166:169], v[190:193], v[92:95]
	v_mfma_f32_16x16x32_bf16 v[84:87], v[154:157], v[198:201], v[84:87]
	v_mfma_f32_16x16x32_bf16 v[76:79], v[166:169], v[198:201], v[76:79]
	v_mfma_f32_16x16x32_bf16 v[112:115], v[202:205], v[170:173], v[112:115]
	v_mfma_f32_16x16x32_bf16 v[104:107], v[210:213], v[170:173], v[104:107]
	v_mfma_f32_16x16x32_bf16 v[96:99], v[202:205], v[178:181], v[96:99]
	v_mfma_f32_16x16x32_bf16 v[88:91], v[210:213], v[178:181], v[88:91]
	v_mfma_f32_16x16x32_bf16 v[80:83], v[202:205], v[186:189], v[80:83]
	v_mfma_f32_16x16x32_bf16 v[72:75], v[210:213], v[186:189], v[72:75]
	v_mfma_f32_16x16x32_bf16 v[68:71], v[202:205], v[194:197], v[68:71]
	v_mfma_f32_16x16x32_bf16 v[64:67], v[210:213], v[194:197], v[64:67]
	v_mfma_f32_16x16x32_bf16 v[112:115], v[206:209], v[174:177], v[112:115]
	v_mfma_f32_16x16x32_bf16 v[104:107], v[214:217], v[174:177], v[104:107]
	v_mfma_f32_16x16x32_bf16 v[96:99], v[206:209], v[182:185], v[96:99]
	v_mfma_f32_16x16x32_bf16 v[88:91], v[214:217], v[182:185], v[88:91]
	v_mfma_f32_16x16x32_bf16 v[80:83], v[206:209], v[190:193], v[80:83]
	v_mfma_f32_16x16x32_bf16 v[72:75], v[214:217], v[190:193], v[72:75]
	v_mfma_f32_16x16x32_bf16 v[68:71], v[206:209], v[198:201], v[68:71]
	v_mfma_f32_16x16x32_bf16 v[64:67], v[214:217], v[198:201], v[64:67]
	s_barrier
	ds_read_b128 v[170:173], v163 offset:16384
	ds_read_b128 v[174:177], v163 offset:17408
	ds_read_b128 v[178:181], v163 offset:18432
	ds_read_b128 v[182:185], v163 offset:19456
	ds_read_b128 v[186:189], v163 offset:20480
	ds_read_b128 v[190:193], v163 offset:21504
	ds_read_b128 v[194:197], v163 offset:22528
	ds_read_b128 v[198:201], v163 offset:23552
	s_add_i32 s45, s66, s21
	s_mov_b32 m0, s45
	v_lshl_add_u64 v[218:219], s[54:55], 0, v[138:139]
	global_load_lds_dwordx4 v[218:219], off
	s_add_i32 m0, s45, 0x2000
	v_lshl_add_u64 v[220:221], s[54:55], 0, v[142:143]
	global_load_lds_dwordx4 v[220:221], off
	s_mov_b32 m0, s33
	v_lshl_add_u64 v[222:223], s[56:57], 0, v[136:137]
	global_load_lds_dwordx4 v[222:223], off
	s_mov_b32 m0, s35
	v_lshl_add_u64 v[224:225], s[56:57], 0, v[140:141]
	global_load_lds_dwordx4 v[224:225], off
	s_add_u32 s78, s54, 0x40000
	s_addc_u32 s79, s55, 0
	s_add_i32 s45, s67, s21
	s_mov_b32 m0, s45
	v_lshl_add_u64 v[240:241], s[78:79], 0, v[138:139]
	global_load_lds_dwordx4 v[240:241], off
	s_add_i32 m0, s45, 0x2000
	v_lshl_add_u64 v[240:241], s[78:79], 0, v[142:143]
	global_load_lds_dwordx4 v[240:241], off
	s_waitcnt vmcnt(8) lgkmcnt(0)
	s_barrier
; #define PG8_STAGE(bufoff, gbase, voff) do { _Pragma("unroll") for (int _i = 0; _i < 2; ++_i) \
;         __builtin_amdgcn_global_load_lds((const unsigned*)((const char*)(gbase) + (voff)[_i]), (LAS unsigned*)(lds + (bufoff) + ldsw + _i * 8192), 16, 0, 0); } while (0)
; #define PG8_LDA(dst, b, h) do { _Pragma("unroll") for (int m = 0; m < 4; ++m) _Pragma("unroll") for (int k = 0; k < 2; ++k) dst[m][k] = *(const LAS bf16x8*)(lds + PG8_SA(b, h) + aoff + m * 2048 + k * 1024); } while (0)
; #define PG8_LDB(dst, b, h) do { _Pragma("unroll") for (int n = 0; n < 2; ++n) _Pragma("unroll") for (int k = 0; k < 2; ++k) dst[n][k] = *(const LAS bf16x8*)(lds + PG8_SB(b, h) + boff + n * 2048 + k * 1024); } while (0)
; #define PG8_MMA(ai, bj, At, Bt) do { __builtin_amdgcn_s_setprio(1); _Pragma("unroll") for (int m = 0; m < 4; ++m) _Pragma("unroll") for (int n = 0; n < 2; ++n) _Pragma("unroll") for (int k = 0; k < 2; ++k) \
;         acc[ai][bj][m][n] = __builtin_amdgcn_mfma_f32_16x16x32_bf16(Bt[n][k], At[m][k], acc[ai][bj][m][n], 0, 0, 0); __builtin_amdgcn_s_setprio(0); } while (0)
; #define PG8_WAIT_V(n) asm volatile("s_waitcnt vmcnt(" #n ")" ::: "memory")
; #define PG8_WAIT_L(n) asm volatile("s_waitcnt lgkmcnt(" #n ")" ::: "memory")
; #define PG8_BAR __builtin_amdgcn_s_barrier()
; #define PG8_SCHED __builtin_amdgcn_sched_barrier(0)
; template <class Epi>
; __device__ __forceinline__ void gemm_phase(LAS unsigned char* lds, const Gemm g, const StaticOrder& S, const Epi& E) {
;     ...
;             PG8_WAIT_V(6); PG8_BAR; PG8_MMA(1, 1, At, B1); PG8_BAR;
;             PG8_LDB(B0, 1, 0); PG8_SCHED; PG8_LDA(At, 1, 0); PG8_STAGE(PG8_SA(0, 1), a2 + hstepA, voffA);
;             PG8_WAIT_L(8); PG8_BAR; PG8_WAIT_L(0); PG8_MMA(0, 0, At, B0); PG8_BAR; PG8_SCHED;
;             PG8_LDB(B1, 1, 1); PG8_STAGE(PG8_SB(1, 0), b3, voffB);
;             PG8_BAR; PG8_WAIT_L(0); PG8_MMA(0, 1, At, B1); PG8_BAR;
;             PG8_LDA(At, 1, 1); PG8_STAGE(PG8_SA(1, 0), a3, voffA);
;             PG8_BAR; PG8_WAIT_L(0); PG8_MMA(1, 0, At, B0); PG8_BAR; PG8_SCHED;
	v_mfma_f32_16x16x32_bf16 v[60:63], v[150:153], v[170:173], v[60:63]
	v_mfma_f32_16x16x32_bf16 v[56:59], v[158:161], v[170:173], v[56:59]
	v_mfma_f32_16x16x32_bf16 v[52:55], v[150:153], v[178:181], v[52:55]
	v_mfma_f32_16x16x32_bf16 v[44:47], v[158:161], v[178:181], v[44:47]
	v_mfma_f32_16x16x32_bf16 v[36:39], v[150:153], v[186:189], v[36:39]
	v_mfma_f32_16x16x32_bf16 v[28:31], v[158:161], v[186:189], v[28:31]
	v_mfma_f32_16x16x32_bf16 v[20:23], v[150:153], v[194:197], v[20:23]
	v_mfma_f32_16x16x32_bf16 v[12:15], v[158:161], v[194:197], v[12:15]
	v_mfma_f32_16x16x32_bf16 v[60:63], v[154:157], v[174:177], v[60:63]
	v_mfma_f32_16x16x32_bf16 v[56:59], v[166:169], v[174:177], v[56:59]
	v_mfma_f32_16x16x32_bf16 v[52:55], v[154:157], v[182:185], v[52:55]
	v_mfma_f32_16x16x32_bf16 v[44:47], v[166:169], v[182:185], v[44:47]
	v_mfma_f32_16x16x32_bf16 v[36:39], v[154:157], v[190:193], v[36:39]
	v_mfma_f32_16x16x32_bf16 v[28:31], v[166:169], v[190:193], v[28:31]
	v_mfma_f32_16x16x32_bf16 v[20:23], v[154:157], v[198:201], v[20:23]
	v_mfma_f32_16x16x32_bf16 v[12:15], v[166:169], v[198:201], v[12:15]
	v_mfma_f32_16x16x32_bf16 v[48:51], v[202:205], v[170:173], v[48:51]
	v_mfma_f32_16x16x32_bf16 v[40:43], v[210:213], v[170:173], v[40:43]
	v_mfma_f32_16x16x32_bf16 v[32:35], v[202:205], v[178:181], v[32:35]
	v_mfma_f32_16x16x32_bf16 v[24:27], v[210:213], v[178:181], v[24:27]
	v_mfma_f32_16x16x32_bf16 v[16:19], v[202:205], v[186:189], v[16:19]
	v_mfma_f32_16x16x32_bf16 v[8:11], v[210:213], v[186:189], v[8:11]
	v_mfma_f32_16x16x32_bf16 v[4:7], v[202:205], v[194:197], v[4:7]
	v_mfma_f32_16x16x32_bf16 v[0:3], v[210:213], v[194:197], v[0:3]
	v_mfma_f32_16x16x32_bf16 v[48:51], v[206:209], v[174:177], v[48:51]
	v_mfma_f32_16x16x32_bf16 v[40:43], v[214:217], v[174:177], v[40:43]
	v_mfma_f32_16x16x32_bf16 v[32:35], v[206:209], v[182:185], v[32:35]
	v_mfma_f32_16x16x32_bf16 v[24:27], v[214:217], v[182:185], v[24:27]
	v_mfma_f32_16x16x32_bf16 v[16:19], v[206:209], v[190:193], v[16:19]
	v_mfma_f32_16x16x32_bf16 v[8:11], v[214:217], v[190:193], v[8:11]
	v_mfma_f32_16x16x32_bf16 v[4:7], v[206:209], v[198:201], v[4:7]
	v_mfma_f32_16x16x32_bf16 v[0:3], v[214:217], v[198:201], v[0:3]
	s_barrier
	s_add_i32 s45, 0, 0x18000
	v_add_u32_e32 v165, s45, v135
	ds_read_b128 v[150:153], v165
	ds_read_b128 v[154:157], v165 offset:1024
	ds_read_b128 v[158:161], v165 offset:2048
	ds_read_b128 v[166:169], v165 offset:3072
	ds_read_b128 v[170:173], v163 offset:32768
	ds_read_b128 v[174:177], v163 offset:33792
	ds_read_b128 v[178:181], v163 offset:34816
	ds_read_b128 v[182:185], v163 offset:35840
	ds_read_b128 v[186:189], v163 offset:36864
	ds_read_b128 v[190:193], v163 offset:37888
	ds_read_b128 v[194:197], v163 offset:38912
	ds_read_b128 v[198:201], v163 offset:39936
	s_add_i32 s98, 0, 0x1c000
	v_add_u32_e32 v246, s98, v135
	ds_read_b128 v[202:205], v246
	ds_read_b128 v[206:209], v246 offset:1024
	ds_read_b128 v[210:213], v246 offset:2048
	ds_read_b128 v[214:217], v246 offset:3072
	s_add_u32 s56, s56, 0x40000
	s_addc_u32 s57, s57, 0
	s_mov_b32 m0, s58
	v_lshl_add_u64 v[244:245], s[56:57], 0, v[136:137]
	global_load_lds_dwordx4 v[244:245], off
	s_mov_b32 m0, s59
	v_lshl_add_u64 v[244:245], s[56:57], 0, v[140:141]
	global_load_lds_dwordx4 v[244:245], off
	s_waitcnt vmcnt(8) lgkmcnt(0)
	s_barrier
	v_mfma_f32_16x16x32_bf16 v[124:127], v[150:153], v[170:173], v[124:127]
	v_mfma_f32_16x16x32_bf16 v[120:123], v[158:161], v[170:173], v[120:123]
	v_mfma_f32_16x16x32_bf16 v[116:119], v[150:153], v[178:181], v[116:119]
	v_mfma_f32_16x16x32_bf16 v[108:111], v[158:161], v[178:181], v[108:111]
	v_mfma_f32_16x16x32_bf16 v[100:103], v[150:153], v[186:189], v[100:103]
	v_mfma_f32_16x16x32_bf16 v[92:95], v[158:161], v[186:189], v[92:95]
	v_mfma_f32_16x16x32_bf16 v[84:87], v[150:153], v[194:197], v[84:87]
	v_mfma_f32_16x16x32_bf16 v[76:79], v[158:161], v[194:197], v[76:79]
	v_mfma_f32_16x16x32_bf16 v[124:127], v[154:157], v[174:177], v[124:127]
	v_mfma_f32_16x16x32_bf16 v[120:123], v[166:169], v[174:177], v[120:123]
	v_mfma_f32_16x16x32_bf16 v[116:119], v[154:157], v[182:185], v[116:119]
	v_mfma_f32_16x16x32_bf16 v[108:111], v[166:169], v[182:185], v[108:111]
	v_mfma_f32_16x16x32_bf16 v[100:103], v[154:157], v[190:193], v[100:103]
	v_mfma_f32_16x16x32_bf16 v[92:95], v[166:169], v[190:193], v[92:95]
	v_mfma_f32_16x16x32_bf16 v[84:87], v[154:157], v[198:201], v[84:87]
	v_mfma_f32_16x16x32_bf16 v[76:79], v[166:169], v[198:201], v[76:79]
	v_mfma_f32_16x16x32_bf16 v[112:115], v[202:205], v[170:173], v[112:115]
	v_mfma_f32_16x16x32_bf16 v[104:107], v[210:213], v[170:173], v[104:107]
	v_mfma_f32_16x16x32_bf16 v[96:99], v[202:205], v[178:181], v[96:99]
	v_mfma_f32_16x16x32_bf16 v[88:91], v[210:213], v[178:181], v[88:91]
	v_mfma_f32_16x16x32_bf16 v[80:83], v[202:205], v[186:189], v[80:83]
	v_mfma_f32_16x16x32_bf16 v[72:75], v[210:213], v[186:189], v[72:75]
	v_mfma_f32_16x16x32_bf16 v[68:71], v[202:205], v[194:197], v[68:71]
	v_mfma_f32_16x16x32_bf16 v[64:67], v[210:213], v[194:197], v[64:67]
	v_mfma_f32_16x16x32_bf16 v[112:115], v[206:209], v[174:177], v[112:115]
	v_mfma_f32_16x16x32_bf16 v[104:107], v[214:217], v[174:177], v[104:107]
	v_mfma_f32_16x16x32_bf16 v[96:99], v[206:209], v[182:185], v[96:99]
	v_mfma_f32_16x16x32_bf16 v[88:91], v[214:217], v[182:185], v[88:91]
	v_mfma_f32_16x16x32_bf16 v[80:83], v[206:209], v[190:193], v[80:83]
	v_mfma_f32_16x16x32_bf16 v[72:75], v[214:217], v[190:193], v[72:75]
	v_mfma_f32_16x16x32_bf16 v[68:71], v[206:209], v[198:201], v[68:71]
	v_mfma_f32_16x16x32_bf16 v[64:67], v[214:217], v[198:201], v[64:67]
	s_barrier
; #define PG8_STAGE(bufoff, gbase, voff) do { _Pragma("unroll") for (int _i = 0; _i < 2; ++_i) \
;         __builtin_amdgcn_global_load_lds((const unsigned*)((const char*)(gbase) + (voff)[_i]), (LAS unsigned*)(lds + (bufoff) + ldsw + _i * 8192), 16, 0, 0); } while (0)
; #define PG8_LDA(dst, b, h) do { _Pragma("unroll") for (int m = 0; m < 4; ++m) _Pragma("unroll") for (int k = 0; k < 2; ++k) dst[m][k] = *(const LAS bf16x8*)(lds + PG8_SA(b, h) + aoff + m * 2048 + k * 1024); } while (0)
; #define PG8_MMA(ai, bj, At, Bt) do { __builtin_amdgcn_s_setprio(1); _Pragma("unroll") for (int m = 0; m < 4; ++m) _Pragma("unroll") for (int n = 0; n < 2; ++n) _Pragma("unroll") for (int k = 0; k < 2; ++k) \
;         acc[ai][bj][m][n] = __builtin_amdgcn_mfma_f32_16x16x32_bf16(Bt[n][k], At[m][k], acc[ai][bj][m][n], 0, 0, 0); __builtin_amdgcn_s_setprio(0); } while (0)
; #define PG8_WAIT_V(n) asm volatile("s_waitcnt vmcnt(" #n ")" ::: "memory")
; #define PG8_WAIT_L(n) asm volatile("s_waitcnt lgkmcnt(" #n ")" ::: "memory")
; #define PG8_BAR __builtin_amdgcn_s_barrier()
; #define PG8_SCHED __builtin_amdgcn_sched_barrier(0)
; template <class Epi>
; __device__ __forceinline__ void gemm_phase(LAS unsigned char* lds, const Gemm g, const StaticOrder& S, const Epi& E) {
;     ...
;             PG8_LDA(At, 1, 1); PG8_STAGE(PG8_SA(1, 0), a3, voffA);
;             PG8_BAR; PG8_WAIT_L(0); PG8_MMA(1, 0, At, B0); PG8_BAR; PG8_SCHED;
;             PG8_STAGE(PG8_SB(1, 1), b3 + hstepB, voffB);
;             PG8_WAIT_V(6); PG8_BAR; PG8_MMA(1, 1, At, B1); PG8_BAR;
;         }
	ds_read_b128 v[170:173], v163 offset:49152
	ds_read_b128 v[174:177], v163 offset:50176
	ds_read_b128 v[178:181], v163 offset:51200
	ds_read_b128 v[182:185], v163 offset:52224
	ds_read_b128 v[186:189], v163 offset:53248
	ds_read_b128 v[190:193], v163 offset:54272
	ds_read_b128 v[194:197], v163 offset:55296
	ds_read_b128 v[198:201], v163 offset:56320
	s_add_i32 s45, s45, s21
	s_mov_b32 m0, s45
	v_lshl_add_u64 v[218:219], v[218:219], 0, s[12:13]
	global_load_lds_dwordx4 v[218:219], off
	s_add_i32 m0, s45, 0x2000
	v_lshl_add_u64 v[218:219], v[220:221], 0, s[12:13]
	global_load_lds_dwordx4 v[218:219], off
	s_mov_b32 m0, s60
	v_lshl_add_u64 v[218:219], v[222:223], 0, s[12:13]
	global_load_lds_dwordx4 v[218:219], off
	s_mov_b32 m0, s61
	v_lshl_add_u64 v[218:219], v[224:225], 0, s[12:13]
	global_load_lds_dwordx4 v[218:219], off
	s_add_u32 s54, s54, 0x40080
	s_addc_u32 s55, s55, 0
	s_add_i32 s45, s98, s21
	s_mov_b32 m0, s45
	v_lshl_add_u64 v[240:241], s[54:55], 0, v[138:139]
	global_load_lds_dwordx4 v[240:241], off
	s_add_i32 m0, s45, 0x2000
	v_lshl_add_u64 v[240:241], s[54:55], 0, v[142:143]
	global_load_lds_dwordx4 v[240:241], off
	s_waitcnt vmcnt(8) lgkmcnt(0)
	s_barrier
	v_mfma_f32_16x16x32_bf16 v[60:63], v[150:153], v[170:173], v[60:63]
	v_mfma_f32_16x16x32_bf16 v[56:59], v[158:161], v[170:173], v[56:59]
	v_mfma_f32_16x16x32_bf16 v[52:55], v[150:153], v[178:181], v[52:55]
	v_mfma_f32_16x16x32_bf16 v[44:47], v[158:161], v[178:181], v[44:47]
	v_mfma_f32_16x16x32_bf16 v[36:39], v[150:153], v[186:189], v[36:39]
	v_mfma_f32_16x16x32_bf16 v[28:31], v[158:161], v[186:189], v[28:31]
	v_mfma_f32_16x16x32_bf16 v[20:23], v[150:153], v[194:197], v[20:23]
	v_mfma_f32_16x16x32_bf16 v[12:15], v[158:161], v[194:197], v[12:15]
	v_mfma_f32_16x16x32_bf16 v[60:63], v[154:157], v[174:177], v[60:63]
	v_mfma_f32_16x16x32_bf16 v[56:59], v[166:169], v[174:177], v[56:59]
	v_mfma_f32_16x16x32_bf16 v[52:55], v[154:157], v[182:185], v[52:55]
	v_mfma_f32_16x16x32_bf16 v[44:47], v[166:169], v[182:185], v[44:47]
	v_mfma_f32_16x16x32_bf16 v[36:39], v[154:157], v[190:193], v[36:39]
	v_mfma_f32_16x16x32_bf16 v[28:31], v[166:169], v[190:193], v[28:31]
	v_mfma_f32_16x16x32_bf16 v[20:23], v[154:157], v[198:201], v[20:23]
	v_mfma_f32_16x16x32_bf16 v[12:15], v[166:169], v[198:201], v[12:15]
	v_mfma_f32_16x16x32_bf16 v[48:51], v[202:205], v[170:173], v[48:51]
	v_mfma_f32_16x16x32_bf16 v[40:43], v[210:213], v[170:173], v[40:43]
	v_mfma_f32_16x16x32_bf16 v[32:35], v[202:205], v[178:181], v[32:35]
	v_mfma_f32_16x16x32_bf16 v[24:27], v[210:213], v[178:181], v[24:27]
	v_mfma_f32_16x16x32_bf16 v[16:19], v[202:205], v[186:189], v[16:19]
	v_mfma_f32_16x16x32_bf16 v[8:11], v[210:213], v[186:189], v[8:11]
	v_mfma_f32_16x16x32_bf16 v[4:7], v[202:205], v[194:197], v[4:7]
	v_mfma_f32_16x16x32_bf16 v[0:3], v[210:213], v[194:197], v[0:3]
	v_mfma_f32_16x16x32_bf16 v[48:51], v[206:209], v[174:177], v[48:51]
	v_mfma_f32_16x16x32_bf16 v[40:43], v[214:217], v[174:177], v[40:43]
	v_mfma_f32_16x16x32_bf16 v[32:35], v[206:209], v[182:185], v[32:35]
	v_mfma_f32_16x16x32_bf16 v[24:27], v[214:217], v[182:185], v[24:27]
	v_mfma_f32_16x16x32_bf16 v[16:19], v[206:209], v[190:193], v[16:19]
	v_mfma_f32_16x16x32_bf16 v[8:11], v[214:217], v[190:193], v[8:11]
	v_mfma_f32_16x16x32_bf16 v[4:7], v[206:209], v[198:201], v[4:7]
	v_mfma_f32_16x16x32_bf16 v[0:3], v[214:217], v[198:201], v[0:3]
	s_add_u32 s50, s50, 0x100
	s_addc_u32 s51, s51, 0
	s_add_u32 s41, s41, 0x100
	s_addc_u32 s43, s43, 0
	s_cmp_ge_i32 s77, s76
	s_mov_b32 s45, s77
	s_cbranch_scc1 .Leo_exit4
	s_barrier
	s_branch .LBB0_1146

;     __device__ __forceinline__ void operator()(const f32x4 (&acc)[2][2][4][2], const Unit& u, int wr, int wc, int fr, int fq) const {
;         const int row0 = u.pm * BM + wr * 64 + fr, col0 = u.pn * BM + wc * 32 + 8 * fq;
;         if (u.part) {
;             float* base = tailacc + (size_t)(u.part - 1) * slab - (size_t)tail_row0 * tail_ld;
; #pragma unroll
;             for (int ai = 0; ai < 2; ++ai)
; #pragma unroll
;                 for (int m = 0; m < 4; ++m) { float* rowp = base + (size_t)(row0 + ai * HALF + m * 16) * tail_ld + col0;
; #pragma unroll
;                     for (int bj = 0; bj < 2; ++bj)
; #pragma unroll
;                         for (int n = 0; n < 2; ++n) *(f32x4*)(rowp + bj * HALF + 4 * n) = acc[ai][bj][m][n]; }
;             return;
.Leo_b4:
	v_lshl_add_u32 v150, s8, 8, v133
	v_lshl_or_b32 v154, s44, 8, v162
	s_cmp_lg_u32 s75, 0
	v_ashrrev_i32_e32 v155, 31, v154
	v_or_b32_e32 v160, 16, v150
	v_or_b32_e32 v158, 32, v150
	v_or_b32_e32 v156, 48, v150
	s_cbranch_scc0 .LBB0_1149
	s_add_i32 s8, s75, -1
	s_lshl_b64 s[44:45], s[8:9], 21
	s_add_u32 s44, s92, s44
	s_addc_u32 s45, s93, s45
	v_lshl_add_u64 v[152:153], v[154:155], 2, s[44:45]
	v_ashrrev_i32_e32 v151, 31, v150
	v_ashrrev_i32_e32 v161, 31, v160
	v_lshl_add_u64 v[152:153], v[152:153], 0, s[22:23]
	v_lshlrev_b64 v[166:167], 12, v[150:151]
	v_lshlrev_b64 v[168:169], 12, v[160:161]
	v_lshl_add_u64 v[166:167], v[152:153], 0, v[166:167]
	v_lshl_add_u64 v[168:169], v[152:153], 0, v[168:169]
	v_ashrrev_i32_e32 v159, 31, v158
	global_store_dwordx4 v[166:167], v[124:127], off
	global_store_dwordx4 v[166:167], v[120:123], off offset:16
	global_store_dwordx4 v[166:167], v[112:115], off offset:512
	global_store_dwordx4 v[166:167], v[104:107], off offset:528
	global_store_dwordx4 v[168:169], v[116:119], off
	global_store_dwordx4 v[168:169], v[108:111], off offset:16
	global_store_dwordx4 v[168:169], v[96:99], off offset:512
	global_store_dwordx4 v[168:169], v[88:91], off offset:528
	v_lshlrev_b64 v[168:169], 12, v[158:159]
	v_lshl_add_u64 v[168:169], v[152:153], 0, v[168:169]
	v_ashrrev_i32_e32 v157, 31, v156
	global_store_dwordx4 v[168:169], v[100:103], off
	global_store_dwordx4 v[168:169], v[92:95], off offset:16
	global_store_dwordx4 v[168:169], v[80:83], off offset:512
	global_store_dwordx4 v[168:169], v[72:75], off offset:528
	v_lshlrev_b64 v[168:169], 12, v[156:157]
	v_lshl_add_u64 v[152:153], v[152:153], 0, v[168:169]
	v_add_co_u32_e32 v168, vcc, s68, v166
	global_store_dwordx4 v[152:153], v[84:87], off
	global_store_dwordx4 v[152:153], v[76:79], off offset:16
	global_store_dwordx4 v[152:153], v[68:71], off offset:512
	global_store_dwordx4 v[152:153], v[64:67], off offset:528
	v_addc_co_u32_e32 v169, vcc, 0, v167, vcc
	v_lshl_add_u64 v[152:153], v[166:167], 0, s[24:25]
	global_store_dwordx4 v[168:169], v[60:63], off
	global_store_dwordx4 v[152:153], v[56:59], off offset:16
	global_store_dwordx4 v[152:153], v[48:51], off offset:512
	global_store_dwordx4 v[152:153], v[40:43], off offset:528
	v_add_co_u32_e32 v168, vcc, s69, v166
	v_lshl_add_u64 v[152:153], v[166:167], 0, s[26:27]
	s_nop 0
	v_addc_co_u32_e32 v169, vcc, 0, v167, vcc
	global_store_dwordx4 v[168:169], v[52:55], off
	global_store_dwordx4 v[152:153], v[44:47], off offset:16
	global_store_dwordx4 v[152:153], v[32:35], off offset:512
	global_store_dwordx4 v[152:153], v[24:27], off offset:528
	v_add_co_u32_e32 v168, vcc, s70, v166
	v_lshl_add_u64 v[152:153], v[166:167], 0, s[28:29]
	s_nop 0
	v_addc_co_u32_e32 v169, vcc, 0, v167, vcc
	global_store_dwordx4 v[168:169], v[36:39], off
	global_store_dwordx4 v[152:153], v[28:31], off offset:16
	global_store_dwordx4 v[152:153], v[16:19], off offset:512
	global_store_dwordx4 v[152:153], v[8:11], off offset:528
	v_lshl_add_u64 v[152:153], v[166:167], 0, s[36:37]
	v_add_co_u32_e32 v166, vcc, 0xb0000, v166
	s_nop 1
	v_addc_co_u32_e32 v167, vcc, 0, v167, vcc
	global_store_dwordx4 v[166:167], v[20:23], off
	global_store_dwordx4 v[152:153], v[12:15], off offset:16
	global_store_dwordx4 v[152:153], v[4:7], off offset:512
	global_store_dwordx4 v[152:153], v[0:3], off offset:528
	s_cbranch_execnz .LBB0_1131
	s_branch .LBB0_1130
